# speedup vs baseline: 1.0116x; 1.0107x over previous
; #define STAGE_A(bufoff, gbase) STAGEX(bufoff, gbase, voffA)
; #define STAGE_B(bufoff, gbase) STAGEX(bufoff, gbase, voffB)
; #define LDA(dst, b, h) do { _Pragma("unroll") for (int m = 0; m < 4; ++m) _Pragma("unroll") for (int k = 0; k < 2; ++k) dst[m][k] = *(const __attribute__((address_space(3))) bf16x8*)(lds + SA(b, h) + aoff + m * 2048 + k * 1024); } while (0)
; #define LDB(dst, b, h) do { _Pragma("unroll") for (int n = 0; n < 2; ++n) _Pragma("unroll") for (int k = 0; k < 2; ++k) dst[n][k] = *(const __attribute__((address_space(3))) bf16x8*)(lds + SB_(b, h) + boff + n * 2048 + k * 1024); } while (0)
; #define MMA(ai, bj, At, Bt_) do { __builtin_amdgcn_s_setprio(1); _Pragma("unroll") for (int m = 0; m < 4; ++m) _Pragma("unroll") for (int n = 0; n < 2; ++n) _Pragma("unroll") for (int k = 0; k < 2; ++k) \
;       acc[ai][bj][m][n] = __builtin_amdgcn_mfma_f32_16x16x32_bf16(Bt_[n][k], At[m][k], acc[ai][bj][m][n], 0, 0, 0); \
;     __builtin_amdgcn_s_setprio(0); } while (0)
; #define WAIT_V(n) asm volatile("s_waitcnt vmcnt(" #n ")" ::: "memory")
; #define BAR __builtin_amdgcn_s_barrier()
; template <int MODE>
; DEV void gemm_phase(const bf16_t* __restrict__ A, const bf16_t* __restrict__ Bt, int M, int N, int K, bf16_t* __restrict__ Out, int ldo,
;                     const float* __restrict__ rstd, const float* __restrict__ rope) {
;     ...
;     for (int t = 0; t < nt; t += 2) {
;       const bool last = (t == nt - 2);
;       const char* a1 = cA + (size_t)(t + 1) * 128;
;       const char* a2 = last ? nA : cA + (size_t)(t + 2) * 128; const char* b2 = last ? nB : cB + (size_t)(t + 2) * 128;
;       const char* a3 = a2 + 128; const char* b3 = b2 + 128;
;       LDB(B0, 0, 0); LDB(B1, 0, 1); SCHED; LDA(At, 0, 0); STAGE_A(SA(1, 1), a1 + hstep);
;       WAIT_V(8); WAIT_L(0); BAR; MMA(0, 0, At, B0); MMA(0, 1, At, B1); BAR; SCHED;
;       LDA(At, 0, 1); STAGE_B(SB_(0, 0), b2); STAGE_B(SB_(0, 1), b2 + hstep); STAGE_A(SA(0, 0), a2);
;       WAIT_V(8); WAIT_L(0); BAR; MMA(1, 0, At, B0); MMA(1, 1, At, B1); BAR; SCHED;
;       LDB(B0, 1, 0); LDB(B1, 1, 1); SCHED; LDA(At, 1, 0); STAGE_A(SA(0, 1), a2 + hstep);
;       WAIT_V(8); WAIT_L(0); BAR; MMA(0, 0, At, B0); MMA(0, 1, At, B1); BAR; SCHED;
;       LDA(At, 1, 1); STAGE_B(SB_(1, 0), b3); STAGE_B(SB_(1, 1), b3 + hstep); STAGE_A(SA(1, 0), a3);
;       WAIT_V(8); WAIT_L(0); BAR; MMA(1, 0, At, B0); MMA(1, 1, At, B1); BAR; SCHED;
.LBB0_128:
	s_add_u32 s26, s44, s8
	s_addc_u32 s27, s45, s9
	s_add_u32 s26, s26, 0x12200100
	s_addc_u32 s27, s27, 0
	s_add_u32 s49, s46, s8
	s_addc_u32 s50, s47, s9
	s_add_i32 s51, 0, 0x10000
	s_cmpk_eq_i32 s8, 0xf00
	s_cselect_b32 s29, s42, s27
	s_cselect_b32 s28, s19, s26
	s_cselect_b32 s27, s43, s50
	s_cselect_b32 s26, s21, s49
	s_add_i32 s49, 0, 0x14000
	v_add_u32_e32 v144, s51, v171
	v_add_u32_e32 v168, s49, v171
	ds_read_b128 v[132:135], v144
	ds_read_b128 v[136:139], v144 offset:1024
	ds_read_b128 v[140:143], v144 offset:2048
	ds_read_b128 v[144:147], v144 offset:3072
	ds_read_b128 v[148:151], v168
	ds_read_b128 v[164:167], v168 offset:1024
	ds_read_b128 v[174:177], v168 offset:2048
	ds_read_b128 v[178:181], v168 offset:3072
	v_lshl_add_u64 v[168:169], v[128:129], 0, s[8:9]
	s_add_i32 m0, s31, 0xc000
	ds_read_b128 v[182:185], v172
	ds_read_b128 v[186:189], v172 offset:1024
	ds_read_b128 v[194:197], v172 offset:2048
	ds_read_b128 v[198:201], v172 offset:3072
	ds_read_b128 v[202:205], v172 offset:4096
	ds_read_b128 v[206:209], v172 offset:5120
	ds_read_b128 v[216:219], v172 offset:6144
	ds_read_b128 v[220:223], v172 offset:7168
	global_load_lds_dwordx4 v[168:169], off
	v_lshl_add_u64 v[168:169], v[130:131], 0, s[8:9]
	s_add_i32 m0, s31, 0xe000
	s_nop 0
	global_load_lds_dwordx4 v[168:169], off
	s_waitcnt vmcnt(8)
	s_waitcnt lgkmcnt(0)
	s_setprio 1
	s_barrier
	v_mfma_f32_16x16x32_bf16 v[124:127], v[132:135], v[182:185], v[124:127]
	v_mfma_f32_16x16x32_bf16 v[120:123], v[140:143], v[182:185], v[120:123]
	v_mfma_f32_16x16x32_bf16 v[108:111], v[132:135], v[194:197], v[108:111]
	v_mfma_f32_16x16x32_bf16 v[104:107], v[140:143], v[194:197], v[104:107]
	v_mfma_f32_16x16x32_bf16 v[92:95], v[132:135], v[202:205], v[92:95]
	v_mfma_f32_16x16x32_bf16 v[88:91], v[140:143], v[202:205], v[88:91]
	v_mfma_f32_16x16x32_bf16 v[76:79], v[132:135], v[216:219], v[76:79]
	v_mfma_f32_16x16x32_bf16 v[72:75], v[140:143], v[216:219], v[72:75]
	v_mfma_f32_16x16x32_bf16 v[124:127], v[136:139], v[186:189], v[124:127]
	v_mfma_f32_16x16x32_bf16 v[120:123], v[144:147], v[186:189], v[120:123]
	v_mfma_f32_16x16x32_bf16 v[108:111], v[136:139], v[198:201], v[108:111]
	v_mfma_f32_16x16x32_bf16 v[104:107], v[144:147], v[198:201], v[104:107]
	v_mfma_f32_16x16x32_bf16 v[92:95], v[136:139], v[206:209], v[92:95]
	v_mfma_f32_16x16x32_bf16 v[88:91], v[144:147], v[206:209], v[88:91]
	v_mfma_f32_16x16x32_bf16 v[76:79], v[136:139], v[220:223], v[76:79]
	v_mfma_f32_16x16x32_bf16 v[72:75], v[144:147], v[220:223], v[72:75]
	s_setprio 0
	s_setprio 1
	v_mfma_f32_16x16x32_bf16 v[116:119], v[148:151], v[182:185], v[116:119]
	v_mfma_f32_16x16x32_bf16 v[112:115], v[174:177], v[182:185], v[112:115]
	v_mfma_f32_16x16x32_bf16 v[100:103], v[148:151], v[194:197], v[100:103]
	v_mfma_f32_16x16x32_bf16 v[96:99], v[174:177], v[194:197], v[96:99]
	v_mfma_f32_16x16x32_bf16 v[84:87], v[148:151], v[202:205], v[84:87]
	v_mfma_f32_16x16x32_bf16 v[80:83], v[174:177], v[202:205], v[80:83]
	v_mfma_f32_16x16x32_bf16 v[68:71], v[148:151], v[216:219], v[68:71]
	v_mfma_f32_16x16x32_bf16 v[64:67], v[174:177], v[216:219], v[64:67]
	v_mfma_f32_16x16x32_bf16 v[116:119], v[164:167], v[186:189], v[116:119]
	v_mfma_f32_16x16x32_bf16 v[112:115], v[178:181], v[186:189], v[112:115]
	v_mfma_f32_16x16x32_bf16 v[100:103], v[164:167], v[198:201], v[100:103]
	v_mfma_f32_16x16x32_bf16 v[96:99], v[178:181], v[198:201], v[96:99]
	v_mfma_f32_16x16x32_bf16 v[84:87], v[164:167], v[206:209], v[84:87]
	v_mfma_f32_16x16x32_bf16 v[80:83], v[178:181], v[206:209], v[80:83]
	v_mfma_f32_16x16x32_bf16 v[68:71], v[164:167], v[220:223], v[68:71]
	v_mfma_f32_16x16x32_bf16 v[64:67], v[178:181], v[220:223], v[64:67]
	s_setprio 0
	s_barrier
	s_add_i32 s50, s51, s30
	v_lshl_add_u64 v[168:169], s[26:27], 0, v[192:193]
	s_mov_b32 m0, s50
	ds_read_b128 v[182:185], v172 offset:16384
	ds_read_b128 v[186:189], v172 offset:17408
	ds_read_b128 v[194:197], v172 offset:18432
	ds_read_b128 v[198:201], v172 offset:19456
	ds_read_b128 v[202:205], v172 offset:20480
	ds_read_b128 v[206:209], v172 offset:21504
	ds_read_b128 v[216:219], v172 offset:22528
	ds_read_b128 v[220:223], v172 offset:23552
	global_load_lds_dwordx4 v[168:169], off
	s_add_i32 m0, s50, 0x2000
	s_add_u32 s50, s26, 0x80000
	v_lshl_add_u64 v[190:191], s[26:27], 0, v[152:153]
	s_addc_u32 s51, s27, 0
	s_add_i32 s49, s49, s30
	global_load_lds_dwordx4 v[190:191], off
	v_lshl_add_u64 v[212:213], s[50:51], 0, v[192:193]
	s_mov_b32 m0, s49
	v_lshl_add_u64 v[214:215], s[28:29], 0, v[154:155]
	global_load_lds_dwordx4 v[212:213], off
	v_lshl_add_u64 v[212:213], s[50:51], 0, v[152:153]
	s_add_i32 m0, s49, 0x2000
	s_nop 0
	global_load_lds_dwordx4 v[212:213], off
	v_lshl_add_u64 v[212:213], s[28:29], 0, v[156:157]
	s_mov_b32 m0, s31
	s_nop 0
	global_load_lds_dwordx4 v[212:213], off
	s_mov_b32 m0, s34
	s_nop 0
	global_load_lds_dwordx4 v[214:215], off
	s_waitcnt vmcnt(8)
	s_waitcnt lgkmcnt(0)
	s_setprio 1
	s_barrier
; #define STAGE_A(bufoff, gbase) STAGEX(bufoff, gbase, voffA)
; #define STAGE_B(bufoff, gbase) STAGEX(bufoff, gbase, voffB)
; #define LDA(dst, b, h) do { _Pragma("unroll") for (int m = 0; m < 4; ++m) _Pragma("unroll") for (int k = 0; k < 2; ++k) dst[m][k] = *(const __attribute__((address_space(3))) bf16x8*)(lds + SA(b, h) + aoff + m * 2048 + k * 1024); } while (0)
; #define LDB(dst, b, h) do { _Pragma("unroll") for (int n = 0; n < 2; ++n) _Pragma("unroll") for (int k = 0; k < 2; ++k) dst[n][k] = *(const __attribute__((address_space(3))) bf16x8*)(lds + SB_(b, h) + boff + n * 2048 + k * 1024); } while (0)
; #define MMA(ai, bj, At, Bt_) do { __builtin_amdgcn_s_setprio(1); _Pragma("unroll") for (int m = 0; m < 4; ++m) _Pragma("unroll") for (int n = 0; n < 2; ++n) _Pragma("unroll") for (int k = 0; k < 2; ++k) \
;       acc[ai][bj][m][n] = __builtin_amdgcn_mfma_f32_16x16x32_bf16(Bt_[n][k], At[m][k], acc[ai][bj][m][n], 0, 0, 0); \
;     __builtin_amdgcn_s_setprio(0); } while (0)
; #define WAIT_V(n) asm volatile("s_waitcnt vmcnt(" #n ")" ::: "memory")
; #define WAIT_L(n) asm volatile("s_waitcnt lgkmcnt(" #n ")" ::: "memory")
; #define BAR __builtin_amdgcn_s_barrier()
; #define SCHED __builtin_amdgcn_sched_barrier(0)
; template <int MODE>
; DEV void gemm_phase(const bf16_t* __restrict__ A, const bf16_t* __restrict__ Bt, int M, int N, int K, bf16_t* __restrict__ Out, int ldo,
;                     const float* __restrict__ rstd, const float* __restrict__ rope) {
;     ...
;       WAIT_V(8); WAIT_L(0); BAR; MMA(0, 0, At, B0); MMA(0, 1, At, B1); BAR; SCHED;
;       LDA(At, 0, 1); STAGE_B(SB_(0, 0), b2); STAGE_B(SB_(0, 1), b2 + hstep); STAGE_A(SA(0, 0), a2);
;       WAIT_V(8); WAIT_L(0); BAR; MMA(1, 0, At, B0); MMA(1, 1, At, B1); BAR; SCHED;
;       LDB(B0, 1, 0); LDB(B1, 1, 1); SCHED; LDA(At, 1, 0); STAGE_A(SA(0, 1), a2 + hstep);
;       WAIT_V(8); WAIT_L(0); BAR; MMA(0, 0, At, B0); MMA(0, 1, At, B1); BAR; SCHED;
	v_mfma_f32_16x16x32_bf16 v[60:63], v[132:135], v[182:185], v[60:63]
	v_mfma_f32_16x16x32_bf16 v[56:59], v[140:143], v[182:185], v[56:59]
	v_mfma_f32_16x16x32_bf16 v[44:47], v[132:135], v[194:197], v[44:47]
	v_mfma_f32_16x16x32_bf16 v[40:43], v[140:143], v[194:197], v[40:43]
	v_mfma_f32_16x16x32_bf16 v[28:31], v[132:135], v[202:205], v[28:31]
	v_mfma_f32_16x16x32_bf16 v[24:27], v[140:143], v[202:205], v[24:27]
	v_mfma_f32_16x16x32_bf16 v[12:15], v[132:135], v[216:219], v[12:15]
	v_mfma_f32_16x16x32_bf16 v[8:11], v[140:143], v[216:219], v[8:11]
	v_mfma_f32_16x16x32_bf16 v[60:63], v[136:139], v[186:189], v[60:63]
	v_mfma_f32_16x16x32_bf16 v[56:59], v[144:147], v[186:189], v[56:59]
	v_mfma_f32_16x16x32_bf16 v[44:47], v[136:139], v[198:201], v[44:47]
	v_mfma_f32_16x16x32_bf16 v[40:43], v[144:147], v[198:201], v[40:43]
	v_mfma_f32_16x16x32_bf16 v[28:31], v[136:139], v[206:209], v[28:31]
	v_mfma_f32_16x16x32_bf16 v[24:27], v[144:147], v[206:209], v[24:27]
	v_mfma_f32_16x16x32_bf16 v[12:15], v[136:139], v[220:223], v[12:15]
	v_mfma_f32_16x16x32_bf16 v[8:11], v[144:147], v[220:223], v[8:11]
	s_setprio 0
	s_setprio 1
	v_mfma_f32_16x16x32_bf16 v[52:55], v[148:151], v[182:185], v[52:55]
	v_mfma_f32_16x16x32_bf16 v[48:51], v[174:177], v[182:185], v[48:51]
	v_mfma_f32_16x16x32_bf16 v[36:39], v[148:151], v[194:197], v[36:39]
	v_mfma_f32_16x16x32_bf16 v[32:35], v[174:177], v[194:197], v[32:35]
	v_mfma_f32_16x16x32_bf16 v[20:23], v[148:151], v[202:205], v[20:23]
	v_mfma_f32_16x16x32_bf16 v[16:19], v[174:177], v[202:205], v[16:19]
	v_mfma_f32_16x16x32_bf16 v[4:7], v[148:151], v[216:219], v[4:7]
	v_mfma_f32_16x16x32_bf16 v[0:3], v[174:177], v[216:219], v[0:3]
	v_mfma_f32_16x16x32_bf16 v[52:55], v[164:167], v[186:189], v[52:55]
	v_mfma_f32_16x16x32_bf16 v[48:51], v[178:181], v[186:189], v[48:51]
	v_mfma_f32_16x16x32_bf16 v[36:39], v[164:167], v[198:201], v[36:39]
	v_mfma_f32_16x16x32_bf16 v[32:35], v[178:181], v[198:201], v[32:35]
	v_mfma_f32_16x16x32_bf16 v[20:23], v[164:167], v[206:209], v[20:23]
	v_mfma_f32_16x16x32_bf16 v[16:19], v[178:181], v[206:209], v[16:19]
	v_mfma_f32_16x16x32_bf16 v[4:7], v[164:167], v[220:223], v[4:7]
	v_mfma_f32_16x16x32_bf16 v[0:3], v[178:181], v[220:223], v[0:3]
	s_setprio 0
	s_barrier
	s_add_i32 s49, 0, 0x18000
	s_add_i32 s50, 0, 0x1c000
	v_add_u32_e32 v144, s49, v171
	v_add_u32_e32 v173, s50, v171
	ds_read_b128 v[132:135], v144
	ds_read_b128 v[136:139], v144 offset:1024
	ds_read_b128 v[140:143], v144 offset:2048
	ds_read_b128 v[144:147], v144 offset:3072
	ds_read_b128 v[148:151], v173
	ds_read_b128 v[164:167], v173 offset:1024
	ds_read_b128 v[174:177], v173 offset:2048
	ds_read_b128 v[178:181], v173 offset:3072
	s_add_u32 s28, s28, 0x80000
	s_addc_u32 s29, s29, 0
	s_mov_b32 m0, s35
	v_lshl_add_u64 v[224:225], s[28:29], 0, v[156:157]
	ds_read_b128 v[182:185], v172 offset:32768
	ds_read_b128 v[186:189], v172 offset:33792
	ds_read_b128 v[194:197], v172 offset:34816
	ds_read_b128 v[198:201], v172 offset:35840
	ds_read_b128 v[202:205], v172 offset:36864
	ds_read_b128 v[206:209], v172 offset:37888
	ds_read_b128 v[216:219], v172 offset:38912
	ds_read_b128 v[220:223], v172 offset:39936
	global_load_lds_dwordx4 v[224:225], off
	v_lshl_add_u64 v[224:225], s[28:29], 0, v[154:155]
	s_mov_b32 m0, s36
	s_nop 0
	global_load_lds_dwordx4 v[224:225], off
	s_waitcnt vmcnt(8)
	s_waitcnt lgkmcnt(0)
	s_setprio 1
	s_barrier
	v_mfma_f32_16x16x32_bf16 v[124:127], v[132:135], v[182:185], v[124:127]
	v_mfma_f32_16x16x32_bf16 v[120:123], v[140:143], v[182:185], v[120:123]
	v_mfma_f32_16x16x32_bf16 v[108:111], v[132:135], v[194:197], v[108:111]
	v_mfma_f32_16x16x32_bf16 v[104:107], v[140:143], v[194:197], v[104:107]
	v_mfma_f32_16x16x32_bf16 v[92:95], v[132:135], v[202:205], v[92:95]
	v_mfma_f32_16x16x32_bf16 v[88:91], v[140:143], v[202:205], v[88:91]
	v_mfma_f32_16x16x32_bf16 v[76:79], v[132:135], v[216:219], v[76:79]
	v_mfma_f32_16x16x32_bf16 v[72:75], v[140:143], v[216:219], v[72:75]
	v_mfma_f32_16x16x32_bf16 v[124:127], v[136:139], v[186:189], v[124:127]
	v_mfma_f32_16x16x32_bf16 v[120:123], v[144:147], v[186:189], v[120:123]
	v_mfma_f32_16x16x32_bf16 v[108:111], v[136:139], v[198:201], v[108:111]
	v_mfma_f32_16x16x32_bf16 v[104:107], v[144:147], v[198:201], v[104:107]
	v_mfma_f32_16x16x32_bf16 v[92:95], v[136:139], v[206:209], v[92:95]
	v_mfma_f32_16x16x32_bf16 v[88:91], v[144:147], v[206:209], v[88:91]
	v_mfma_f32_16x16x32_bf16 v[76:79], v[136:139], v[220:223], v[76:79]
	v_mfma_f32_16x16x32_bf16 v[72:75], v[144:147], v[220:223], v[72:75]
	s_setprio 0
	s_setprio 1
	v_mfma_f32_16x16x32_bf16 v[116:119], v[148:151], v[182:185], v[116:119]
	v_mfma_f32_16x16x32_bf16 v[112:115], v[174:177], v[182:185], v[112:115]
	v_mfma_f32_16x16x32_bf16 v[100:103], v[148:151], v[194:197], v[100:103]
	v_mfma_f32_16x16x32_bf16 v[96:99], v[174:177], v[194:197], v[96:99]
	v_mfma_f32_16x16x32_bf16 v[84:87], v[148:151], v[202:205], v[84:87]
	v_mfma_f32_16x16x32_bf16 v[80:83], v[174:177], v[202:205], v[80:83]
	v_mfma_f32_16x16x32_bf16 v[68:71], v[148:151], v[216:219], v[68:71]
	v_mfma_f32_16x16x32_bf16 v[64:67], v[174:177], v[216:219], v[64:67]
	v_mfma_f32_16x16x32_bf16 v[116:119], v[164:167], v[186:189], v[116:119]
	v_mfma_f32_16x16x32_bf16 v[112:115], v[178:181], v[186:189], v[112:115]
	v_mfma_f32_16x16x32_bf16 v[100:103], v[164:167], v[198:201], v[100:103]
	v_mfma_f32_16x16x32_bf16 v[96:99], v[178:181], v[198:201], v[96:99]
	v_mfma_f32_16x16x32_bf16 v[84:87], v[164:167], v[206:209], v[84:87]
	v_mfma_f32_16x16x32_bf16 v[80:83], v[178:181], v[206:209], v[80:83]
	v_mfma_f32_16x16x32_bf16 v[68:71], v[164:167], v[220:223], v[68:71]
	v_mfma_f32_16x16x32_bf16 v[64:67], v[178:181], v[220:223], v[64:67]
	s_setprio 0
	s_barrier
; #define STAGE_A(bufoff, gbase) STAGEX(bufoff, gbase, voffA)
; #define STAGE_B(bufoff, gbase) STAGEX(bufoff, gbase, voffB)
; #define LDA(dst, b, h) do { _Pragma("unroll") for (int m = 0; m < 4; ++m) _Pragma("unroll") for (int k = 0; k < 2; ++k) dst[m][k] = *(const __attribute__((address_space(3))) bf16x8*)(lds + SA(b, h) + aoff + m * 2048 + k * 1024); } while (0)
; #define MMA(ai, bj, At, Bt_) do { __builtin_amdgcn_s_setprio(1); _Pragma("unroll") for (int m = 0; m < 4; ++m) _Pragma("unroll") for (int n = 0; n < 2; ++n) _Pragma("unroll") for (int k = 0; k < 2; ++k) \
;       acc[ai][bj][m][n] = __builtin_amdgcn_mfma_f32_16x16x32_bf16(Bt_[n][k], At[m][k], acc[ai][bj][m][n], 0, 0, 0); \
;     __builtin_amdgcn_s_setprio(0); } while (0)
; #define WAIT_V(n) asm volatile("s_waitcnt vmcnt(" #n ")" ::: "memory")
; #define WAIT_L(n) asm volatile("s_waitcnt lgkmcnt(" #n ")" ::: "memory")
; #define BAR __builtin_amdgcn_s_barrier()
; #define SCHED __builtin_amdgcn_sched_barrier(0)
; template <int MODE>
; DEV void gemm_phase(const bf16_t* __restrict__ A, const bf16_t* __restrict__ Bt, int M, int N, int K, bf16_t* __restrict__ Out, int ldo,
;                     const float* __restrict__ rstd, const float* __restrict__ rope) {
;     ...
;       WAIT_V(8); WAIT_L(0); BAR; MMA(0, 0, At, B0); MMA(0, 1, At, B1); BAR; SCHED;
;       LDA(At, 1, 1); STAGE_B(SB_(1, 0), b3); STAGE_B(SB_(1, 1), b3 + hstep); STAGE_A(SA(1, 0), a3);
;       WAIT_V(8); WAIT_L(0); BAR; MMA(1, 0, At, B0); MMA(1, 1, At, B1); BAR; SCHED;
;     }
	s_add_i32 s28, s49, s30
	v_lshl_add_u64 v[168:169], v[168:169], 0, s[88:89]
	s_mov_b32 m0, s28
	ds_read_b128 v[182:185], v172 offset:49152
	ds_read_b128 v[186:189], v172 offset:50176
	ds_read_b128 v[194:197], v172 offset:51200
	ds_read_b128 v[198:201], v172 offset:52224
	ds_read_b128 v[202:205], v172 offset:53248
	ds_read_b128 v[206:209], v172 offset:54272
	ds_read_b128 v[216:219], v172 offset:55296
	ds_read_b128 v[220:223], v172 offset:56320
	global_load_lds_dwordx4 v[168:169], off
	s_add_i32 m0, s28, 0x2000
	s_add_u32 s26, s26, 0x80080
	v_lshl_add_u64 v[168:169], v[190:191], 0, s[88:89]
	s_addc_u32 s27, s27, 0
	s_add_i32 s28, s50, s30
	global_load_lds_dwordx4 v[168:169], off
	v_lshl_add_u64 v[168:169], s[26:27], 0, v[192:193]
	s_mov_b32 m0, s28
	s_nop 0
	global_load_lds_dwordx4 v[168:169], off
	v_lshl_add_u64 v[168:169], s[26:27], 0, v[152:153]
	s_add_i32 m0, s28, 0x2000
	s_nop 0
	global_load_lds_dwordx4 v[168:169], off
	v_lshl_add_u64 v[168:169], v[212:213], 0, s[88:89]
	s_mov_b32 m0, s37
	s_nop 0
	global_load_lds_dwordx4 v[168:169], off
	v_lshl_add_u64 v[168:169], v[214:215], 0, s[88:89]
	s_mov_b32 m0, s38
	s_nop 0
	global_load_lds_dwordx4 v[168:169], off
	s_waitcnt vmcnt(8)
	s_waitcnt lgkmcnt(0)
	s_setprio 1
	s_barrier
	v_mfma_f32_16x16x32_bf16 v[60:63], v[132:135], v[182:185], v[60:63]
	v_mfma_f32_16x16x32_bf16 v[56:59], v[140:143], v[182:185], v[56:59]
	v_mfma_f32_16x16x32_bf16 v[44:47], v[132:135], v[194:197], v[44:47]
	v_mfma_f32_16x16x32_bf16 v[40:43], v[140:143], v[194:197], v[40:43]
	v_mfma_f32_16x16x32_bf16 v[28:31], v[132:135], v[202:205], v[28:31]
	v_mfma_f32_16x16x32_bf16 v[24:27], v[140:143], v[202:205], v[24:27]
	v_mfma_f32_16x16x32_bf16 v[12:15], v[132:135], v[216:219], v[12:15]
	v_mfma_f32_16x16x32_bf16 v[8:11], v[140:143], v[216:219], v[8:11]
	v_mfma_f32_16x16x32_bf16 v[60:63], v[136:139], v[186:189], v[60:63]
	v_mfma_f32_16x16x32_bf16 v[56:59], v[144:147], v[186:189], v[56:59]
	v_mfma_f32_16x16x32_bf16 v[44:47], v[136:139], v[198:201], v[44:47]
	v_mfma_f32_16x16x32_bf16 v[40:43], v[144:147], v[198:201], v[40:43]
	v_mfma_f32_16x16x32_bf16 v[28:31], v[136:139], v[206:209], v[28:31]
	v_mfma_f32_16x16x32_bf16 v[24:27], v[144:147], v[206:209], v[24:27]
	v_mfma_f32_16x16x32_bf16 v[12:15], v[136:139], v[220:223], v[12:15]
	v_mfma_f32_16x16x32_bf16 v[8:11], v[144:147], v[220:223], v[8:11]
	s_setprio 0
	s_setprio 1
	v_mfma_f32_16x16x32_bf16 v[52:55], v[148:151], v[182:185], v[52:55]
	v_mfma_f32_16x16x32_bf16 v[48:51], v[174:177], v[182:185], v[48:51]
	v_mfma_f32_16x16x32_bf16 v[36:39], v[148:151], v[194:197], v[36:39]
	v_mfma_f32_16x16x32_bf16 v[32:35], v[174:177], v[194:197], v[32:35]
	v_mfma_f32_16x16x32_bf16 v[20:23], v[148:151], v[202:205], v[20:23]
	v_mfma_f32_16x16x32_bf16 v[16:19], v[174:177], v[202:205], v[16:19]
	v_mfma_f32_16x16x32_bf16 v[4:7], v[148:151], v[216:219], v[4:7]
	v_mfma_f32_16x16x32_bf16 v[0:3], v[174:177], v[216:219], v[0:3]
	v_mfma_f32_16x16x32_bf16 v[52:55], v[164:167], v[186:189], v[52:55]
	v_mfma_f32_16x16x32_bf16 v[48:51], v[178:181], v[186:189], v[48:51]
	v_mfma_f32_16x16x32_bf16 v[36:39], v[164:167], v[198:201], v[36:39]
	v_mfma_f32_16x16x32_bf16 v[32:35], v[178:181], v[198:201], v[32:35]
	v_mfma_f32_16x16x32_bf16 v[20:23], v[164:167], v[206:209], v[20:23]
	v_mfma_f32_16x16x32_bf16 v[16:19], v[178:181], v[206:209], v[16:19]
	v_mfma_f32_16x16x32_bf16 v[4:7], v[164:167], v[220:223], v[4:7]
	v_mfma_f32_16x16x32_bf16 v[0:3], v[178:181], v[220:223], v[0:3]
	s_setprio 0
	s_barrier
	s_add_i32 s48, s48, 2
	s_add_u32 s8, s8, 0x100
	s_addc_u32 s9, s9, 0
	s_cmp_gt_u32 s48, 29
	s_cbranch_scc0 .LBB0_128
	s_and_b64 vcc, exec, s[12:13]
	s_cbranch_vccz .LBB0_131
	s_barrier

; #define STAGE_A(bufoff, gbase) STAGEX(bufoff, gbase, voffA)
; #define STAGE_B(bufoff, gbase) STAGEX(bufoff, gbase, voffB)
; #define LDA(dst, b, h) do { _Pragma("unroll") for (int m = 0; m < 4; ++m) _Pragma("unroll") for (int k = 0; k < 2; ++k) dst[m][k] = *(const __attribute__((address_space(3))) bf16x8*)(lds + SA(b, h) + aoff + m * 2048 + k * 1024); } while (0)
; #define LDB(dst, b, h) do { _Pragma("unroll") for (int n = 0; n < 2; ++n) _Pragma("unroll") for (int k = 0; k < 2; ++k) dst[n][k] = *(const __attribute__((address_space(3))) bf16x8*)(lds + SB_(b, h) + boff + n * 2048 + k * 1024); } while (0)
; #define MMA(ai, bj, At, Bt_) do { __builtin_amdgcn_s_setprio(1); _Pragma("unroll") for (int m = 0; m < 4; ++m) _Pragma("unroll") for (int n = 0; n < 2; ++n) _Pragma("unroll") for (int k = 0; k < 2; ++k) \
;       acc[ai][bj][m][n] = __builtin_amdgcn_mfma_f32_16x16x32_bf16(Bt_[n][k], At[m][k], acc[ai][bj][m][n], 0, 0, 0); \
;     __builtin_amdgcn_s_setprio(0); } while (0)
; #define WAIT_V(n) asm volatile("s_waitcnt vmcnt(" #n ")" ::: "memory")
; #define BAR __builtin_amdgcn_s_barrier()
; template <int MODE>
; DEV void gemm_phase(const bf16_t* __restrict__ A, const bf16_t* __restrict__ Bt, int M, int N, int K, bf16_t* __restrict__ Out, int ldo,
;                     const float* __restrict__ rstd, const float* __restrict__ rope) {
;     ...
;     for (int t = 0; t < nt; t += 2) {
;       const bool last = (t == nt - 2);
;       const char* a1 = cA + (size_t)(t + 1) * 128;
;       const char* a2 = last ? nA : cA + (size_t)(t + 2) * 128; const char* b2 = last ? nB : cB + (size_t)(t + 2) * 128;
;       const char* a3 = a2 + 128; const char* b3 = b2 + 128;
;       LDB(B0, 0, 0); LDB(B1, 0, 1); SCHED; LDA(At, 0, 0); STAGE_A(SA(1, 1), a1 + hstep);
;       WAIT_V(8); WAIT_L(0); BAR; MMA(0, 0, At, B0); MMA(0, 1, At, B1); BAR; SCHED;
;       LDA(At, 0, 1); STAGE_B(SB_(0, 0), b2); STAGE_B(SB_(0, 1), b2 + hstep); STAGE_A(SA(0, 0), a2);
;       WAIT_V(8); WAIT_L(0); BAR; MMA(1, 0, At, B0); MMA(1, 1, At, B1); BAR; SCHED;
;       LDB(B0, 1, 0); LDB(B1, 1, 1); SCHED; LDA(At, 1, 0); STAGE_A(SA(0, 1), a2 + hstep);
;       WAIT_V(8); WAIT_L(0); BAR; MMA(0, 0, At, B0); MMA(0, 1, At, B1); BAR; SCHED;
;       LDA(At, 1, 1); STAGE_B(SB_(1, 0), b3); STAGE_B(SB_(1, 1), b3 + hstep); STAGE_A(SA(1, 0), a3);
;       WAIT_V(8); WAIT_L(0); BAR; MMA(1, 0, At, B0); MMA(1, 1, At, B1); BAR; SCHED;
.LBB0_493:
	s_add_u32 s20, s18, 0xfff80080
	s_addc_u32 s21, s19, -1
	s_add_i32 s39, 0, 0x10000
	s_cmp_eq_u32 s38, 28
	s_cselect_b32 s23, s15, s21
	s_cselect_b32 s22, s14, s20
	v_add_u32_e32 v143, s39, v141
	s_cselect_b32 s21, s13, s37
	s_cselect_b32 s20, s11, s36
	s_add_i32 s42, 0, 0x14000
	ds_read_b128 v[144:147], v143
	ds_read_b128 v[148:151], v143 offset:1024
	ds_read_b128 v[152:155], v143 offset:2048
	ds_read_b128 v[156:159], v143 offset:3072
	v_add_u32_e32 v143, s42, v141
	ds_read_b128 v[160:163], v143
	ds_read_b128 v[164:167], v143 offset:1024
	ds_read_b128 v[168:171], v143 offset:2048
	ds_read_b128 v[172:175], v143 offset:3072
	v_lshl_add_u64 v[212:213], s[18:19], 0, v[136:137]
	s_add_i32 m0, s25, 0xc000
	ds_read_b128 v[176:179], v142
	ds_read_b128 v[180:183], v142 offset:1024
	ds_read_b128 v[184:187], v142 offset:2048
	ds_read_b128 v[188:191], v142 offset:3072
	ds_read_b128 v[194:197], v142 offset:4096
	ds_read_b128 v[198:201], v142 offset:5120
	ds_read_b128 v[202:205], v142 offset:6144
	ds_read_b128 v[206:209], v142 offset:7168
	global_load_lds_dwordx4 v[212:213], off
	v_lshl_add_u64 v[212:213], s[18:19], 0, v[138:139]
	s_add_i32 m0, s25, 0xe000
	s_nop 0
	global_load_lds_dwordx4 v[212:213], off
	s_waitcnt vmcnt(8)
	s_waitcnt lgkmcnt(0)
	s_setprio 1
	s_barrier
	v_mfma_f32_16x16x32_bf16 v[124:127], v[144:147], v[176:179], v[124:127]
	v_mfma_f32_16x16x32_bf16 v[120:123], v[152:155], v[176:179], v[120:123]
	v_mfma_f32_16x16x32_bf16 v[116:119], v[144:147], v[184:187], v[116:119]
	v_mfma_f32_16x16x32_bf16 v[112:115], v[152:155], v[184:187], v[112:115]
	v_mfma_f32_16x16x32_bf16 v[100:103], v[144:147], v[194:197], v[100:103]
	v_mfma_f32_16x16x32_bf16 v[96:99], v[152:155], v[194:197], v[96:99]
	v_mfma_f32_16x16x32_bf16 v[84:87], v[144:147], v[202:205], v[84:87]
	v_mfma_f32_16x16x32_bf16 v[80:83], v[152:155], v[202:205], v[80:83]
	v_mfma_f32_16x16x32_bf16 v[124:127], v[148:151], v[180:183], v[124:127]
	v_mfma_f32_16x16x32_bf16 v[120:123], v[156:159], v[180:183], v[120:123]
	v_mfma_f32_16x16x32_bf16 v[116:119], v[148:151], v[188:191], v[116:119]
	v_mfma_f32_16x16x32_bf16 v[112:115], v[156:159], v[188:191], v[112:115]
	v_mfma_f32_16x16x32_bf16 v[100:103], v[148:151], v[198:201], v[100:103]
	v_mfma_f32_16x16x32_bf16 v[96:99], v[156:159], v[198:201], v[96:99]
	v_mfma_f32_16x16x32_bf16 v[84:87], v[148:151], v[206:209], v[84:87]
	v_mfma_f32_16x16x32_bf16 v[80:83], v[156:159], v[206:209], v[80:83]
	s_setprio 0
	s_setprio 1
	v_mfma_f32_16x16x32_bf16 v[108:111], v[160:163], v[176:179], v[108:111]
	v_mfma_f32_16x16x32_bf16 v[104:107], v[168:171], v[176:179], v[104:107]
	v_mfma_f32_16x16x32_bf16 v[92:95], v[160:163], v[184:187], v[92:95]
	v_mfma_f32_16x16x32_bf16 v[88:91], v[168:171], v[184:187], v[88:91]
	v_mfma_f32_16x16x32_bf16 v[76:79], v[160:163], v[194:197], v[76:79]
	v_mfma_f32_16x16x32_bf16 v[72:75], v[168:171], v[194:197], v[72:75]
	v_mfma_f32_16x16x32_bf16 v[68:71], v[160:163], v[202:205], v[68:71]
	v_mfma_f32_16x16x32_bf16 v[64:67], v[168:171], v[202:205], v[64:67]
	v_mfma_f32_16x16x32_bf16 v[108:111], v[164:167], v[180:183], v[108:111]
	v_mfma_f32_16x16x32_bf16 v[104:107], v[172:175], v[180:183], v[104:107]
	v_mfma_f32_16x16x32_bf16 v[92:95], v[164:167], v[188:191], v[92:95]
	v_mfma_f32_16x16x32_bf16 v[88:91], v[172:175], v[188:191], v[88:91]
	v_mfma_f32_16x16x32_bf16 v[76:79], v[164:167], v[198:201], v[76:79]
	v_mfma_f32_16x16x32_bf16 v[72:75], v[172:175], v[198:201], v[72:75]
	v_mfma_f32_16x16x32_bf16 v[68:71], v[164:167], v[206:209], v[68:71]
	v_mfma_f32_16x16x32_bf16 v[64:67], v[172:175], v[206:209], v[64:67]
	s_setprio 0
	s_barrier
	s_add_i32 s39, s39, s24
	v_lshl_add_u64 v[212:213], s[20:21], 0, v[192:193]
	s_mov_b32 m0, s39
	ds_read_b128 v[176:179], v142 offset:16384
	ds_read_b128 v[180:183], v142 offset:17408
	ds_read_b128 v[184:187], v142 offset:18432
	ds_read_b128 v[188:191], v142 offset:19456
	ds_read_b128 v[194:197], v142 offset:20480
	ds_read_b128 v[198:201], v142 offset:21504
	ds_read_b128 v[202:205], v142 offset:22528
	ds_read_b128 v[206:209], v142 offset:23552
	global_load_lds_dwordx4 v[212:213], off
	s_add_i32 m0, s39, 0x2000
	s_add_u32 s40, s20, 0x80000
	v_lshl_add_u64 v[214:215], s[20:21], 0, v[128:129]
	s_addc_u32 s41, s21, 0
	s_add_i32 s39, s42, s24
	global_load_lds_dwordx4 v[214:215], off
	v_lshl_add_u64 v[222:223], s[40:41], 0, v[192:193]
	s_mov_b32 m0, s39
	v_lshl_add_u64 v[224:225], s[22:23], 0, v[130:131]
	global_load_lds_dwordx4 v[222:223], off
	v_lshl_add_u64 v[222:223], s[40:41], 0, v[128:129]
	s_add_i32 m0, s39, 0x2000
	s_nop 0
	global_load_lds_dwordx4 v[222:223], off
	v_lshl_add_u64 v[222:223], s[22:23], 0, v[132:133]
	s_mov_b32 m0, s25
	s_nop 0
	global_load_lds_dwordx4 v[222:223], off
	s_mov_b32 m0, s26
	s_nop 0
	global_load_lds_dwordx4 v[224:225], off
	s_waitcnt vmcnt(8)
	s_waitcnt lgkmcnt(0)
	s_setprio 1
	s_barrier
; #define STAGE_A(bufoff, gbase) STAGEX(bufoff, gbase, voffA)
; #define STAGE_B(bufoff, gbase) STAGEX(bufoff, gbase, voffB)
; #define LDA(dst, b, h) do { _Pragma("unroll") for (int m = 0; m < 4; ++m) _Pragma("unroll") for (int k = 0; k < 2; ++k) dst[m][k] = *(const __attribute__((address_space(3))) bf16x8*)(lds + SA(b, h) + aoff + m * 2048 + k * 1024); } while (0)
; #define LDB(dst, b, h) do { _Pragma("unroll") for (int n = 0; n < 2; ++n) _Pragma("unroll") for (int k = 0; k < 2; ++k) dst[n][k] = *(const __attribute__((address_space(3))) bf16x8*)(lds + SB_(b, h) + boff + n * 2048 + k * 1024); } while (0)
; #define MMA(ai, bj, At, Bt_) do { __builtin_amdgcn_s_setprio(1); _Pragma("unroll") for (int m = 0; m < 4; ++m) _Pragma("unroll") for (int n = 0; n < 2; ++n) _Pragma("unroll") for (int k = 0; k < 2; ++k) \
;       acc[ai][bj][m][n] = __builtin_amdgcn_mfma_f32_16x16x32_bf16(Bt_[n][k], At[m][k], acc[ai][bj][m][n], 0, 0, 0); \
;     __builtin_amdgcn_s_setprio(0); } while (0)
; #define WAIT_V(n) asm volatile("s_waitcnt vmcnt(" #n ")" ::: "memory")
; #define WAIT_L(n) asm volatile("s_waitcnt lgkmcnt(" #n ")" ::: "memory")
; #define BAR __builtin_amdgcn_s_barrier()
; #define SCHED __builtin_amdgcn_sched_barrier(0)
; template <int MODE>
; DEV void gemm_phase(const bf16_t* __restrict__ A, const bf16_t* __restrict__ Bt, int M, int N, int K, bf16_t* __restrict__ Out, int ldo,
;                     const float* __restrict__ rstd, const float* __restrict__ rope) {
;     ...
;       WAIT_V(8); WAIT_L(0); BAR; MMA(0, 0, At, B0); MMA(0, 1, At, B1); BAR; SCHED;
;       LDA(At, 0, 1); STAGE_B(SB_(0, 0), b2); STAGE_B(SB_(0, 1), b2 + hstep); STAGE_A(SA(0, 0), a2);
;       WAIT_V(8); WAIT_L(0); BAR; MMA(1, 0, At, B0); MMA(1, 1, At, B1); BAR; SCHED;
;       LDB(B0, 1, 0); LDB(B1, 1, 1); SCHED; LDA(At, 1, 0); STAGE_A(SA(0, 1), a2 + hstep);
;       WAIT_V(8); WAIT_L(0); BAR; MMA(0, 0, At, B0); MMA(0, 1, At, B1); BAR; SCHED;
	v_mfma_f32_16x16x32_bf16 v[60:63], v[144:147], v[176:179], v[60:63]
	v_mfma_f32_16x16x32_bf16 v[56:59], v[152:155], v[176:179], v[56:59]
	v_mfma_f32_16x16x32_bf16 v[52:55], v[144:147], v[184:187], v[52:55]
	v_mfma_f32_16x16x32_bf16 v[48:51], v[152:155], v[184:187], v[48:51]
	v_mfma_f32_16x16x32_bf16 v[36:39], v[144:147], v[194:197], v[36:39]
	v_mfma_f32_16x16x32_bf16 v[32:35], v[152:155], v[194:197], v[32:35]
	v_mfma_f32_16x16x32_bf16 v[20:23], v[144:147], v[202:205], v[20:23]
	v_mfma_f32_16x16x32_bf16 v[16:19], v[152:155], v[202:205], v[16:19]
	v_mfma_f32_16x16x32_bf16 v[60:63], v[148:151], v[180:183], v[60:63]
	v_mfma_f32_16x16x32_bf16 v[56:59], v[156:159], v[180:183], v[56:59]
	v_mfma_f32_16x16x32_bf16 v[52:55], v[148:151], v[188:191], v[52:55]
	v_mfma_f32_16x16x32_bf16 v[48:51], v[156:159], v[188:191], v[48:51]
	v_mfma_f32_16x16x32_bf16 v[36:39], v[148:151], v[198:201], v[36:39]
	v_mfma_f32_16x16x32_bf16 v[32:35], v[156:159], v[198:201], v[32:35]
	v_mfma_f32_16x16x32_bf16 v[20:23], v[148:151], v[206:209], v[20:23]
	v_mfma_f32_16x16x32_bf16 v[16:19], v[156:159], v[206:209], v[16:19]
	s_setprio 0
	s_setprio 1
	v_mfma_f32_16x16x32_bf16 v[44:47], v[160:163], v[176:179], v[44:47]
	v_mfma_f32_16x16x32_bf16 v[40:43], v[168:171], v[176:179], v[40:43]
	v_mfma_f32_16x16x32_bf16 v[28:31], v[160:163], v[184:187], v[28:31]
	v_mfma_f32_16x16x32_bf16 v[24:27], v[168:171], v[184:187], v[24:27]
	v_mfma_f32_16x16x32_bf16 v[12:15], v[160:163], v[194:197], v[12:15]
	v_mfma_f32_16x16x32_bf16 v[8:11], v[168:171], v[194:197], v[8:11]
	v_mfma_f32_16x16x32_bf16 v[4:7], v[160:163], v[202:205], v[4:7]
	v_mfma_f32_16x16x32_bf16 v[0:3], v[168:171], v[202:205], v[0:3]
	v_mfma_f32_16x16x32_bf16 v[44:47], v[164:167], v[180:183], v[44:47]
	v_mfma_f32_16x16x32_bf16 v[40:43], v[172:175], v[180:183], v[40:43]
	v_mfma_f32_16x16x32_bf16 v[28:31], v[164:167], v[188:191], v[28:31]
	v_mfma_f32_16x16x32_bf16 v[24:27], v[172:175], v[188:191], v[24:27]
	v_mfma_f32_16x16x32_bf16 v[12:15], v[164:167], v[198:201], v[12:15]
	v_mfma_f32_16x16x32_bf16 v[8:11], v[172:175], v[198:201], v[8:11]
	v_mfma_f32_16x16x32_bf16 v[4:7], v[164:167], v[206:209], v[4:7]
	v_mfma_f32_16x16x32_bf16 v[0:3], v[172:175], v[206:209], v[0:3]
	s_setprio 0
	s_barrier
	s_add_i32 s39, 0, 0x18000
	v_add_u32_e32 v143, s39, v141
	s_add_i32 s40, 0, 0x1c000
	ds_read_b128 v[144:147], v143
	ds_read_b128 v[148:151], v143 offset:1024
	ds_read_b128 v[152:155], v143 offset:2048
	ds_read_b128 v[156:159], v143 offset:3072
	v_add_u32_e32 v143, s40, v141
	ds_read_b128 v[160:163], v143
	ds_read_b128 v[164:167], v143 offset:1024
	ds_read_b128 v[168:171], v143 offset:2048
	ds_read_b128 v[172:175], v143 offset:3072
	s_add_u32 s22, s22, 0x80000
	s_addc_u32 s23, s23, 0
	s_mov_b32 m0, s27
	v_lshl_add_u64 v[226:227], s[22:23], 0, v[132:133]
	ds_read_b128 v[176:179], v142 offset:32768
	ds_read_b128 v[180:183], v142 offset:33792
	ds_read_b128 v[184:187], v142 offset:34816
	ds_read_b128 v[188:191], v142 offset:35840
	ds_read_b128 v[194:197], v142 offset:36864
	ds_read_b128 v[198:201], v142 offset:37888
	ds_read_b128 v[202:205], v142 offset:38912
	ds_read_b128 v[206:209], v142 offset:39936
	global_load_lds_dwordx4 v[226:227], off
	v_lshl_add_u64 v[226:227], s[22:23], 0, v[130:131]
	s_mov_b32 m0, s28
	s_nop 0
	global_load_lds_dwordx4 v[226:227], off
	s_waitcnt vmcnt(8)
	s_waitcnt lgkmcnt(0)
	s_setprio 1
	s_barrier
	v_mfma_f32_16x16x32_bf16 v[124:127], v[144:147], v[176:179], v[124:127]
	v_mfma_f32_16x16x32_bf16 v[120:123], v[152:155], v[176:179], v[120:123]
	v_mfma_f32_16x16x32_bf16 v[116:119], v[144:147], v[184:187], v[116:119]
	v_mfma_f32_16x16x32_bf16 v[112:115], v[152:155], v[184:187], v[112:115]
	v_mfma_f32_16x16x32_bf16 v[100:103], v[144:147], v[194:197], v[100:103]
	v_mfma_f32_16x16x32_bf16 v[96:99], v[152:155], v[194:197], v[96:99]
	v_mfma_f32_16x16x32_bf16 v[84:87], v[144:147], v[202:205], v[84:87]
	v_mfma_f32_16x16x32_bf16 v[80:83], v[152:155], v[202:205], v[80:83]
	v_mfma_f32_16x16x32_bf16 v[124:127], v[148:151], v[180:183], v[124:127]
	v_mfma_f32_16x16x32_bf16 v[120:123], v[156:159], v[180:183], v[120:123]
	v_mfma_f32_16x16x32_bf16 v[116:119], v[148:151], v[188:191], v[116:119]
	v_mfma_f32_16x16x32_bf16 v[112:115], v[156:159], v[188:191], v[112:115]
	v_mfma_f32_16x16x32_bf16 v[100:103], v[148:151], v[198:201], v[100:103]
	v_mfma_f32_16x16x32_bf16 v[96:99], v[156:159], v[198:201], v[96:99]
	v_mfma_f32_16x16x32_bf16 v[84:87], v[148:151], v[206:209], v[84:87]
	v_mfma_f32_16x16x32_bf16 v[80:83], v[156:159], v[206:209], v[80:83]
	s_setprio 0
	s_setprio 1
	v_mfma_f32_16x16x32_bf16 v[108:111], v[160:163], v[176:179], v[108:111]
	v_mfma_f32_16x16x32_bf16 v[104:107], v[168:171], v[176:179], v[104:107]
	v_mfma_f32_16x16x32_bf16 v[92:95], v[160:163], v[184:187], v[92:95]
	v_mfma_f32_16x16x32_bf16 v[88:91], v[168:171], v[184:187], v[88:91]
	v_mfma_f32_16x16x32_bf16 v[76:79], v[160:163], v[194:197], v[76:79]
	v_mfma_f32_16x16x32_bf16 v[72:75], v[168:171], v[194:197], v[72:75]
	v_mfma_f32_16x16x32_bf16 v[68:71], v[160:163], v[202:205], v[68:71]
	v_mfma_f32_16x16x32_bf16 v[64:67], v[168:171], v[202:205], v[64:67]
	v_mfma_f32_16x16x32_bf16 v[108:111], v[164:167], v[180:183], v[108:111]
	v_mfma_f32_16x16x32_bf16 v[104:107], v[172:175], v[180:183], v[104:107]
	v_mfma_f32_16x16x32_bf16 v[92:95], v[164:167], v[188:191], v[92:95]
	v_mfma_f32_16x16x32_bf16 v[88:91], v[172:175], v[188:191], v[88:91]
	v_mfma_f32_16x16x32_bf16 v[76:79], v[164:167], v[198:201], v[76:79]
	v_mfma_f32_16x16x32_bf16 v[72:75], v[172:175], v[198:201], v[72:75]
	v_mfma_f32_16x16x32_bf16 v[68:71], v[164:167], v[206:209], v[68:71]
	v_mfma_f32_16x16x32_bf16 v[64:67], v[172:175], v[206:209], v[64:67]
	s_setprio 0
	s_barrier
; #define STAGE_A(bufoff, gbase) STAGEX(bufoff, gbase, voffA)
; #define STAGE_B(bufoff, gbase) STAGEX(bufoff, gbase, voffB)
; #define LDA(dst, b, h) do { _Pragma("unroll") for (int m = 0; m < 4; ++m) _Pragma("unroll") for (int k = 0; k < 2; ++k) dst[m][k] = *(const __attribute__((address_space(3))) bf16x8*)(lds + SA(b, h) + aoff + m * 2048 + k * 1024); } while (0)
; #define MMA(ai, bj, At, Bt_) do { __builtin_amdgcn_s_setprio(1); _Pragma("unroll") for (int m = 0; m < 4; ++m) _Pragma("unroll") for (int n = 0; n < 2; ++n) _Pragma("unroll") for (int k = 0; k < 2; ++k) \
;       acc[ai][bj][m][n] = __builtin_amdgcn_mfma_f32_16x16x32_bf16(Bt_[n][k], At[m][k], acc[ai][bj][m][n], 0, 0, 0); \
;     __builtin_amdgcn_s_setprio(0); } while (0)
; #define WAIT_V(n) asm volatile("s_waitcnt vmcnt(" #n ")" ::: "memory")
; #define WAIT_L(n) asm volatile("s_waitcnt lgkmcnt(" #n ")" ::: "memory")
; #define BAR __builtin_amdgcn_s_barrier()
; #define SCHED __builtin_amdgcn_sched_barrier(0)
; template <int MODE>
; DEV void gemm_phase(const bf16_t* __restrict__ A, const bf16_t* __restrict__ Bt, int M, int N, int K, bf16_t* __restrict__ Out, int ldo,
;                     const float* __restrict__ rstd, const float* __restrict__ rope) {
;     ...
;       WAIT_V(8); WAIT_L(0); BAR; MMA(0, 0, At, B0); MMA(0, 1, At, B1); BAR; SCHED;
;       LDA(At, 1, 1); STAGE_B(SB_(1, 0), b3); STAGE_B(SB_(1, 1), b3 + hstep); STAGE_A(SA(1, 0), a3);
;       WAIT_V(8); WAIT_L(0); BAR; MMA(1, 0, At, B0); MMA(1, 1, At, B1); BAR; SCHED;
;     }
	s_add_i32 s22, s39, s24
	v_lshl_add_u64 v[212:213], v[212:213], 0, s[44:45]
	s_mov_b32 m0, s22
	ds_read_b128 v[176:179], v142 offset:49152
	ds_read_b128 v[180:183], v142 offset:50176
	ds_read_b128 v[184:187], v142 offset:51200
	ds_read_b128 v[188:191], v142 offset:52224
	ds_read_b128 v[194:197], v142 offset:53248
	ds_read_b128 v[198:201], v142 offset:54272
	ds_read_b128 v[202:205], v142 offset:55296
	ds_read_b128 v[206:209], v142 offset:56320
	global_load_lds_dwordx4 v[212:213], off
	s_add_i32 m0, s22, 0x2000
	s_add_u32 s20, s20, 0x80080
	v_lshl_add_u64 v[212:213], v[214:215], 0, s[44:45]
	s_addc_u32 s21, s21, 0
	s_add_i32 s22, s40, s24
	global_load_lds_dwordx4 v[212:213], off
	v_lshl_add_u64 v[212:213], s[20:21], 0, v[192:193]
	s_mov_b32 m0, s22
	s_nop 0
	global_load_lds_dwordx4 v[212:213], off
	v_lshl_add_u64 v[212:213], s[20:21], 0, v[128:129]
	s_add_i32 m0, s22, 0x2000
	s_nop 0
	global_load_lds_dwordx4 v[212:213], off
	v_lshl_add_u64 v[212:213], v[222:223], 0, s[44:45]
	s_mov_b32 m0, s29
	s_nop 0
	global_load_lds_dwordx4 v[212:213], off
	v_lshl_add_u64 v[212:213], v[224:225], 0, s[44:45]
	s_mov_b32 m0, s30
	s_nop 0
	global_load_lds_dwordx4 v[212:213], off
	s_waitcnt vmcnt(8)
	s_waitcnt lgkmcnt(0)
	s_setprio 1
	s_barrier
	v_mfma_f32_16x16x32_bf16 v[60:63], v[144:147], v[176:179], v[60:63]
	v_mfma_f32_16x16x32_bf16 v[56:59], v[152:155], v[176:179], v[56:59]
	v_mfma_f32_16x16x32_bf16 v[52:55], v[144:147], v[184:187], v[52:55]
	v_mfma_f32_16x16x32_bf16 v[48:51], v[152:155], v[184:187], v[48:51]
	v_mfma_f32_16x16x32_bf16 v[36:39], v[144:147], v[194:197], v[36:39]
	v_mfma_f32_16x16x32_bf16 v[32:35], v[152:155], v[194:197], v[32:35]
	v_mfma_f32_16x16x32_bf16 v[20:23], v[144:147], v[202:205], v[20:23]
	v_mfma_f32_16x16x32_bf16 v[16:19], v[152:155], v[202:205], v[16:19]
	v_mfma_f32_16x16x32_bf16 v[60:63], v[148:151], v[180:183], v[60:63]
	v_mfma_f32_16x16x32_bf16 v[56:59], v[156:159], v[180:183], v[56:59]
	v_mfma_f32_16x16x32_bf16 v[52:55], v[148:151], v[188:191], v[52:55]
	v_mfma_f32_16x16x32_bf16 v[48:51], v[156:159], v[188:191], v[48:51]
	v_mfma_f32_16x16x32_bf16 v[36:39], v[148:151], v[198:201], v[36:39]
	v_mfma_f32_16x16x32_bf16 v[32:35], v[156:159], v[198:201], v[32:35]
	v_mfma_f32_16x16x32_bf16 v[20:23], v[148:151], v[206:209], v[20:23]
	v_mfma_f32_16x16x32_bf16 v[16:19], v[156:159], v[206:209], v[16:19]
	s_setprio 0
	s_setprio 1
	v_mfma_f32_16x16x32_bf16 v[44:47], v[160:163], v[176:179], v[44:47]
	v_mfma_f32_16x16x32_bf16 v[40:43], v[168:171], v[176:179], v[40:43]
	v_mfma_f32_16x16x32_bf16 v[28:31], v[160:163], v[184:187], v[28:31]
	v_mfma_f32_16x16x32_bf16 v[24:27], v[168:171], v[184:187], v[24:27]
	v_mfma_f32_16x16x32_bf16 v[12:15], v[160:163], v[194:197], v[12:15]
	v_mfma_f32_16x16x32_bf16 v[8:11], v[168:171], v[194:197], v[8:11]
	v_mfma_f32_16x16x32_bf16 v[4:7], v[160:163], v[202:205], v[4:7]
	v_mfma_f32_16x16x32_bf16 v[0:3], v[168:171], v[202:205], v[0:3]
	v_mfma_f32_16x16x32_bf16 v[44:47], v[164:167], v[180:183], v[44:47]
	v_mfma_f32_16x16x32_bf16 v[40:43], v[172:175], v[180:183], v[40:43]
	v_mfma_f32_16x16x32_bf16 v[28:31], v[164:167], v[188:191], v[28:31]
	v_mfma_f32_16x16x32_bf16 v[24:27], v[172:175], v[188:191], v[24:27]
	v_mfma_f32_16x16x32_bf16 v[12:15], v[164:167], v[198:201], v[12:15]
	v_mfma_f32_16x16x32_bf16 v[8:11], v[172:175], v[198:201], v[8:11]
	v_mfma_f32_16x16x32_bf16 v[4:7], v[164:167], v[206:209], v[4:7]
	v_mfma_f32_16x16x32_bf16 v[0:3], v[172:175], v[206:209], v[0:3]
	s_setprio 0
	s_barrier
	s_add_i32 s38, s38, 2
	s_add_u32 s18, s18, 0x100
	s_addc_u32 s19, s19, 0
	s_add_u32 s36, s36, 0x100
	s_addc_u32 s37, s37, 0
	s_cmp_gt_u32 s38, 29
	s_cbranch_scc0 .LBB0_493
	s_and_b64 vcc, exec, s[6:7]
	s_cbranch_vccz .LBB0_496
	s_barrier

; #define STAGE_A(bufoff, gbase) STAGEX(bufoff, gbase, voffA)
; #define STAGE_B(bufoff, gbase) STAGEX(bufoff, gbase, voffB)
; #define LDA(dst, b, h) do { _Pragma("unroll") for (int m = 0; m < 4; ++m) _Pragma("unroll") for (int k = 0; k < 2; ++k) dst[m][k] = *(const __attribute__((address_space(3))) bf16x8*)(lds + SA(b, h) + aoff + m * 2048 + k * 1024); } while (0)
; #define LDB(dst, b, h) do { _Pragma("unroll") for (int n = 0; n < 2; ++n) _Pragma("unroll") for (int k = 0; k < 2; ++k) dst[n][k] = *(const __attribute__((address_space(3))) bf16x8*)(lds + SB_(b, h) + boff + n * 2048 + k * 1024); } while (0)
; #define MMA(ai, bj, At, Bt_) do { __builtin_amdgcn_s_setprio(1); _Pragma("unroll") for (int m = 0; m < 4; ++m) _Pragma("unroll") for (int n = 0; n < 2; ++n) _Pragma("unroll") for (int k = 0; k < 2; ++k) \
;       acc[ai][bj][m][n] = __builtin_amdgcn_mfma_f32_16x16x32_bf16(Bt_[n][k], At[m][k], acc[ai][bj][m][n], 0, 0, 0); \
;     __builtin_amdgcn_s_setprio(0); } while (0)
; #define WAIT_V(n) asm volatile("s_waitcnt vmcnt(" #n ")" ::: "memory")
; #define BAR __builtin_amdgcn_s_barrier()
; template <int MODE>
; DEV void gemm_phase(const bf16_t* __restrict__ A, const bf16_t* __restrict__ Bt, int M, int N, int K, bf16_t* __restrict__ Out, int ldo,
;                     const float* __restrict__ rstd, const float* __restrict__ rope) {
;     ...
;     for (int t = 0; t < nt; t += 2) {
;       const bool last = (t == nt - 2);
;       const char* a1 = cA + (size_t)(t + 1) * 128;
;       const char* a2 = last ? nA : cA + (size_t)(t + 2) * 128; const char* b2 = last ? nB : cB + (size_t)(t + 2) * 128;
;       const char* a3 = a2 + 128; const char* b3 = b2 + 128;
;       LDB(B0, 0, 0); LDB(B1, 0, 1); SCHED; LDA(At, 0, 0); STAGE_A(SA(1, 1), a1 + hstep);
;       WAIT_V(8); WAIT_L(0); BAR; MMA(0, 0, At, B0); MMA(0, 1, At, B1); BAR; SCHED;
;       LDA(At, 0, 1); STAGE_B(SB_(0, 0), b2); STAGE_B(SB_(0, 1), b2 + hstep); STAGE_A(SA(0, 0), a2);
;       WAIT_V(8); WAIT_L(0); BAR; MMA(1, 0, At, B0); MMA(1, 1, At, B1); BAR; SCHED;
;       LDB(B0, 1, 0); LDB(B1, 1, 1); SCHED; LDA(At, 1, 0); STAGE_A(SA(0, 1), a2 + hstep);
;       WAIT_V(8); WAIT_L(0); BAR; MMA(0, 0, At, B0); MMA(0, 1, At, B1); BAR; SCHED;
;       LDA(At, 1, 1); STAGE_B(SB_(1, 0), b3); STAGE_B(SB_(1, 1), b3 + hstep); STAGE_A(SA(1, 0), a3);
;       WAIT_V(8); WAIT_L(0); BAR; MMA(1, 0, At, B0); MMA(1, 1, At, B1); BAR; SCHED;
.LBB0_618:
	s_add_u32 s20, s38, s18
	s_addc_u32 s21, s39, s19
	s_add_u32 s20, s20, 0x12200100
	s_addc_u32 s21, s21, 0
	s_add_u32 s43, s40, s18
	s_addc_u32 s44, s41, s19
	s_add_i32 s45, 0, 0x10000
	s_cmpk_eq_i32 s18, 0xf00
	s_cselect_b32 s23, s36, s21
	s_cselect_b32 s22, s9, s20
	v_add_u32_e32 v147, s45, v145
	s_cselect_b32 s21, s37, s44
	s_cselect_b32 s20, s11, s43
	s_add_i32 s43, 0, 0x14000
	ds_read_b128 v[148:151], v147
	ds_read_b128 v[152:155], v147 offset:1024
	ds_read_b128 v[156:159], v147 offset:2048
	ds_read_b128 v[160:163], v147 offset:3072
	v_add_u32_e32 v147, s43, v145
	ds_read_b128 v[164:167], v147
	ds_read_b128 v[168:171], v147 offset:1024
	ds_read_b128 v[172:175], v147 offset:2048
	ds_read_b128 v[176:179], v147 offset:3072
	v_lshl_add_u64 v[222:223], v[140:141], 0, s[18:19]
	s_add_i32 m0, s25, 0xc000
	ds_read_b128 v[180:183], v146
	ds_read_b128 v[184:187], v146 offset:1024
	ds_read_b128 v[188:191], v146 offset:2048
	ds_read_b128 v[194:197], v146 offset:3072
	ds_read_b128 v[198:201], v146 offset:4096
	ds_read_b128 v[202:205], v146 offset:5120
	ds_read_b128 v[206:209], v146 offset:6144
	ds_read_b128 v[212:215], v146 offset:7168
	global_load_lds_dwordx4 v[222:223], off
	v_lshl_add_u64 v[222:223], v[142:143], 0, s[18:19]
	s_add_i32 m0, s25, 0xe000
	s_nop 0
	global_load_lds_dwordx4 v[222:223], off
	s_waitcnt vmcnt(8)
	s_waitcnt lgkmcnt(0)
	s_setprio 1
	s_barrier
	v_mfma_f32_16x16x32_bf16 v[124:127], v[148:151], v[180:183], v[124:127]
	v_mfma_f32_16x16x32_bf16 v[120:123], v[156:159], v[180:183], v[120:123]
	v_mfma_f32_16x16x32_bf16 v[108:111], v[148:151], v[188:191], v[108:111]
	v_mfma_f32_16x16x32_bf16 v[104:107], v[156:159], v[188:191], v[104:107]
	v_mfma_f32_16x16x32_bf16 v[92:95], v[148:151], v[198:201], v[92:95]
	v_mfma_f32_16x16x32_bf16 v[88:91], v[156:159], v[198:201], v[88:91]
	v_mfma_f32_16x16x32_bf16 v[76:79], v[148:151], v[206:209], v[76:79]
	v_mfma_f32_16x16x32_bf16 v[72:75], v[156:159], v[206:209], v[72:75]
	v_mfma_f32_16x16x32_bf16 v[124:127], v[152:155], v[184:187], v[124:127]
	v_mfma_f32_16x16x32_bf16 v[120:123], v[160:163], v[184:187], v[120:123]
	v_mfma_f32_16x16x32_bf16 v[108:111], v[152:155], v[194:197], v[108:111]
	v_mfma_f32_16x16x32_bf16 v[104:107], v[160:163], v[194:197], v[104:107]
	v_mfma_f32_16x16x32_bf16 v[92:95], v[152:155], v[202:205], v[92:95]
	v_mfma_f32_16x16x32_bf16 v[88:91], v[160:163], v[202:205], v[88:91]
	v_mfma_f32_16x16x32_bf16 v[76:79], v[152:155], v[212:215], v[76:79]
	v_mfma_f32_16x16x32_bf16 v[72:75], v[160:163], v[212:215], v[72:75]
	s_setprio 0
	s_setprio 1
	v_mfma_f32_16x16x32_bf16 v[116:119], v[164:167], v[180:183], v[116:119]
	v_mfma_f32_16x16x32_bf16 v[112:115], v[172:175], v[180:183], v[112:115]
	v_mfma_f32_16x16x32_bf16 v[100:103], v[164:167], v[188:191], v[100:103]
	v_mfma_f32_16x16x32_bf16 v[96:99], v[172:175], v[188:191], v[96:99]
	v_mfma_f32_16x16x32_bf16 v[84:87], v[164:167], v[198:201], v[84:87]
	v_mfma_f32_16x16x32_bf16 v[80:83], v[172:175], v[198:201], v[80:83]
	v_mfma_f32_16x16x32_bf16 v[68:71], v[164:167], v[206:209], v[68:71]
	v_mfma_f32_16x16x32_bf16 v[64:67], v[172:175], v[206:209], v[64:67]
	v_mfma_f32_16x16x32_bf16 v[116:119], v[168:171], v[184:187], v[116:119]
	v_mfma_f32_16x16x32_bf16 v[112:115], v[176:179], v[184:187], v[112:115]
	v_mfma_f32_16x16x32_bf16 v[100:103], v[168:171], v[194:197], v[100:103]
	v_mfma_f32_16x16x32_bf16 v[96:99], v[176:179], v[194:197], v[96:99]
	v_mfma_f32_16x16x32_bf16 v[84:87], v[168:171], v[202:205], v[84:87]
	v_mfma_f32_16x16x32_bf16 v[80:83], v[176:179], v[202:205], v[80:83]
	v_mfma_f32_16x16x32_bf16 v[68:71], v[168:171], v[212:215], v[68:71]
	v_mfma_f32_16x16x32_bf16 v[64:67], v[176:179], v[212:215], v[64:67]
	s_setprio 0
	s_barrier
	s_add_i32 s44, s45, s24
	v_lshl_add_u64 v[222:223], s[20:21], 0, v[192:193]
	s_mov_b32 m0, s44
	ds_read_b128 v[180:183], v146 offset:16384
	ds_read_b128 v[184:187], v146 offset:17408
	ds_read_b128 v[188:191], v146 offset:18432
	ds_read_b128 v[194:197], v146 offset:19456
	ds_read_b128 v[198:201], v146 offset:20480
	ds_read_b128 v[202:205], v146 offset:21504
	ds_read_b128 v[206:209], v146 offset:22528
	ds_read_b128 v[212:215], v146 offset:23552
	global_load_lds_dwordx4 v[222:223], off
	s_add_i32 m0, s44, 0x2000
	s_add_u32 s44, s20, 0x80000
	v_lshl_add_u64 v[224:225], s[20:21], 0, v[128:129]
	s_addc_u32 s45, s21, 0
	s_add_i32 s43, s43, s24
	global_load_lds_dwordx4 v[224:225], off
	v_lshl_add_u64 v[226:227], s[44:45], 0, v[192:193]
	s_mov_b32 m0, s43
	v_lshl_add_u64 v[228:229], s[22:23], 0, v[130:131]
	global_load_lds_dwordx4 v[226:227], off
	v_lshl_add_u64 v[226:227], s[44:45], 0, v[128:129]
	s_add_i32 m0, s43, 0x2000
	s_nop 0
	global_load_lds_dwordx4 v[226:227], off
	v_lshl_add_u64 v[226:227], s[22:23], 0, v[132:133]
	s_mov_b32 m0, s25
	s_nop 0
	global_load_lds_dwordx4 v[226:227], off
	s_mov_b32 m0, s26
	s_nop 0
	global_load_lds_dwordx4 v[228:229], off
	s_waitcnt vmcnt(8)
	s_waitcnt lgkmcnt(0)
	s_setprio 1
	s_barrier
; #define STAGE_A(bufoff, gbase) STAGEX(bufoff, gbase, voffA)
; #define STAGE_B(bufoff, gbase) STAGEX(bufoff, gbase, voffB)
; #define LDA(dst, b, h) do { _Pragma("unroll") for (int m = 0; m < 4; ++m) _Pragma("unroll") for (int k = 0; k < 2; ++k) dst[m][k] = *(const __attribute__((address_space(3))) bf16x8*)(lds + SA(b, h) + aoff + m * 2048 + k * 1024); } while (0)
; #define LDB(dst, b, h) do { _Pragma("unroll") for (int n = 0; n < 2; ++n) _Pragma("unroll") for (int k = 0; k < 2; ++k) dst[n][k] = *(const __attribute__((address_space(3))) bf16x8*)(lds + SB_(b, h) + boff + n * 2048 + k * 1024); } while (0)
; #define MMA(ai, bj, At, Bt_) do { __builtin_amdgcn_s_setprio(1); _Pragma("unroll") for (int m = 0; m < 4; ++m) _Pragma("unroll") for (int n = 0; n < 2; ++n) _Pragma("unroll") for (int k = 0; k < 2; ++k) \
;       acc[ai][bj][m][n] = __builtin_amdgcn_mfma_f32_16x16x32_bf16(Bt_[n][k], At[m][k], acc[ai][bj][m][n], 0, 0, 0); \
;     __builtin_amdgcn_s_setprio(0); } while (0)
; #define WAIT_V(n) asm volatile("s_waitcnt vmcnt(" #n ")" ::: "memory")
; #define WAIT_L(n) asm volatile("s_waitcnt lgkmcnt(" #n ")" ::: "memory")
; #define BAR __builtin_amdgcn_s_barrier()
; #define SCHED __builtin_amdgcn_sched_barrier(0)
; template <int MODE>
; DEV void gemm_phase(const bf16_t* __restrict__ A, const bf16_t* __restrict__ Bt, int M, int N, int K, bf16_t* __restrict__ Out, int ldo,
;                     const float* __restrict__ rstd, const float* __restrict__ rope) {
;     ...
;       LDB(B0, 0, 0); LDB(B1, 0, 1); SCHED; LDA(At, 0, 0); STAGE_A(SA(1, 1), a1 + hstep);
;       WAIT_V(8); WAIT_L(0); BAR; MMA(0, 0, At, B0); MMA(0, 1, At, B1); BAR; SCHED;
;       LDA(At, 0, 1); STAGE_B(SB_(0, 0), b2); STAGE_B(SB_(0, 1), b2 + hstep); STAGE_A(SA(0, 0), a2);
;       WAIT_V(8); WAIT_L(0); BAR; MMA(1, 0, At, B0); MMA(1, 1, At, B1); BAR; SCHED;
;       LDB(B0, 1, 0); LDB(B1, 1, 1); SCHED; LDA(At, 1, 0); STAGE_A(SA(0, 1), a2 + hstep);
;       WAIT_V(8); WAIT_L(0); BAR; MMA(0, 0, At, B0); MMA(0, 1, At, B1); BAR; SCHED;
;       LDA(At, 1, 1); STAGE_B(SB_(1, 0), b3); STAGE_B(SB_(1, 1), b3 + hstep); STAGE_A(SA(1, 0), a3);
;       WAIT_V(8); WAIT_L(0); BAR; MMA(1, 0, At, B0); MMA(1, 1, At, B1); BAR; SCHED;
	v_mfma_f32_16x16x32_bf16 v[60:63], v[148:151], v[180:183], v[60:63]
	v_mfma_f32_16x16x32_bf16 v[56:59], v[156:159], v[180:183], v[56:59]
	v_mfma_f32_16x16x32_bf16 v[44:47], v[148:151], v[188:191], v[44:47]
	v_mfma_f32_16x16x32_bf16 v[40:43], v[156:159], v[188:191], v[40:43]
	v_mfma_f32_16x16x32_bf16 v[28:31], v[148:151], v[198:201], v[28:31]
	v_mfma_f32_16x16x32_bf16 v[24:27], v[156:159], v[198:201], v[24:27]
	v_mfma_f32_16x16x32_bf16 v[12:15], v[148:151], v[206:209], v[12:15]
	v_mfma_f32_16x16x32_bf16 v[4:7], v[156:159], v[206:209], v[4:7]
	v_mfma_f32_16x16x32_bf16 v[60:63], v[152:155], v[184:187], v[60:63]
	v_mfma_f32_16x16x32_bf16 v[56:59], v[160:163], v[184:187], v[56:59]
	v_mfma_f32_16x16x32_bf16 v[44:47], v[152:155], v[194:197], v[44:47]
	v_mfma_f32_16x16x32_bf16 v[40:43], v[160:163], v[194:197], v[40:43]
	v_mfma_f32_16x16x32_bf16 v[28:31], v[152:155], v[202:205], v[28:31]
	v_mfma_f32_16x16x32_bf16 v[24:27], v[160:163], v[202:205], v[24:27]
	v_mfma_f32_16x16x32_bf16 v[12:15], v[152:155], v[212:215], v[12:15]
	v_mfma_f32_16x16x32_bf16 v[4:7], v[160:163], v[212:215], v[4:7]
	s_setprio 0
	s_setprio 1
	v_mfma_f32_16x16x32_bf16 v[52:55], v[164:167], v[180:183], v[52:55]
	v_mfma_f32_16x16x32_bf16 v[48:51], v[172:175], v[180:183], v[48:51]
	v_mfma_f32_16x16x32_bf16 v[36:39], v[164:167], v[188:191], v[36:39]
	v_mfma_f32_16x16x32_bf16 v[32:35], v[172:175], v[188:191], v[32:35]
	v_mfma_f32_16x16x32_bf16 v[20:23], v[164:167], v[198:201], v[20:23]
	v_mfma_f32_16x16x32_bf16 v[16:19], v[172:175], v[198:201], v[16:19]
	v_mfma_f32_16x16x32_bf16 v[8:11], v[164:167], v[206:209], v[8:11]
	v_mfma_f32_16x16x32_bf16 v[0:3], v[172:175], v[206:209], v[0:3]
	v_mfma_f32_16x16x32_bf16 v[52:55], v[168:171], v[184:187], v[52:55]
	v_mfma_f32_16x16x32_bf16 v[48:51], v[176:179], v[184:187], v[48:51]
	v_mfma_f32_16x16x32_bf16 v[36:39], v[168:171], v[194:197], v[36:39]
	v_mfma_f32_16x16x32_bf16 v[32:35], v[176:179], v[194:197], v[32:35]
	v_mfma_f32_16x16x32_bf16 v[20:23], v[168:171], v[202:205], v[20:23]
	v_mfma_f32_16x16x32_bf16 v[16:19], v[176:179], v[202:205], v[16:19]
	v_mfma_f32_16x16x32_bf16 v[8:11], v[168:171], v[212:215], v[8:11]
	v_mfma_f32_16x16x32_bf16 v[0:3], v[176:179], v[212:215], v[0:3]
	s_setprio 0
	s_barrier
	s_add_i32 s43, 0, 0x18000
	v_add_u32_e32 v147, s43, v145
	s_add_i32 s44, 0, 0x1c000
	ds_read_b128 v[148:151], v147
	ds_read_b128 v[152:155], v147 offset:1024
	ds_read_b128 v[156:159], v147 offset:2048
	ds_read_b128 v[160:163], v147 offset:3072
	v_add_u32_e32 v147, s44, v145
	ds_read_b128 v[164:167], v147
	ds_read_b128 v[168:171], v147 offset:1024
	ds_read_b128 v[172:175], v147 offset:2048
	ds_read_b128 v[176:179], v147 offset:3072
	s_add_u32 s22, s22, 0x80000
	s_addc_u32 s23, s23, 0
	s_mov_b32 m0, s27
	v_lshl_add_u64 v[230:231], s[22:23], 0, v[132:133]
	ds_read_b128 v[180:183], v146 offset:32768
	ds_read_b128 v[184:187], v146 offset:33792
	ds_read_b128 v[188:191], v146 offset:34816
	ds_read_b128 v[194:197], v146 offset:35840
	ds_read_b128 v[198:201], v146 offset:36864
	ds_read_b128 v[202:205], v146 offset:37888
	ds_read_b128 v[206:209], v146 offset:38912
	ds_read_b128 v[212:215], v146 offset:39936
	global_load_lds_dwordx4 v[230:231], off
	v_lshl_add_u64 v[230:231], s[22:23], 0, v[130:131]
	s_mov_b32 m0, s28
	s_nop 0
	global_load_lds_dwordx4 v[230:231], off
	s_waitcnt vmcnt(8)
	s_waitcnt lgkmcnt(0)
	s_setprio 1
	s_barrier
	v_mfma_f32_16x16x32_bf16 v[124:127], v[148:151], v[180:183], v[124:127]
	v_mfma_f32_16x16x32_bf16 v[120:123], v[156:159], v[180:183], v[120:123]
	v_mfma_f32_16x16x32_bf16 v[108:111], v[148:151], v[188:191], v[108:111]
	v_mfma_f32_16x16x32_bf16 v[104:107], v[156:159], v[188:191], v[104:107]
	v_mfma_f32_16x16x32_bf16 v[92:95], v[148:151], v[198:201], v[92:95]
	v_mfma_f32_16x16x32_bf16 v[88:91], v[156:159], v[198:201], v[88:91]
	v_mfma_f32_16x16x32_bf16 v[76:79], v[148:151], v[206:209], v[76:79]
	v_mfma_f32_16x16x32_bf16 v[72:75], v[156:159], v[206:209], v[72:75]
	v_mfma_f32_16x16x32_bf16 v[124:127], v[152:155], v[184:187], v[124:127]
	v_mfma_f32_16x16x32_bf16 v[120:123], v[160:163], v[184:187], v[120:123]
	v_mfma_f32_16x16x32_bf16 v[108:111], v[152:155], v[194:197], v[108:111]
	v_mfma_f32_16x16x32_bf16 v[104:107], v[160:163], v[194:197], v[104:107]
	v_mfma_f32_16x16x32_bf16 v[92:95], v[152:155], v[202:205], v[92:95]
	v_mfma_f32_16x16x32_bf16 v[88:91], v[160:163], v[202:205], v[88:91]
	v_mfma_f32_16x16x32_bf16 v[76:79], v[152:155], v[212:215], v[76:79]
	v_mfma_f32_16x16x32_bf16 v[72:75], v[160:163], v[212:215], v[72:75]
	s_setprio 0
	s_setprio 1
	v_mfma_f32_16x16x32_bf16 v[116:119], v[164:167], v[180:183], v[116:119]
	v_mfma_f32_16x16x32_bf16 v[112:115], v[172:175], v[180:183], v[112:115]
	v_mfma_f32_16x16x32_bf16 v[100:103], v[164:167], v[188:191], v[100:103]
	v_mfma_f32_16x16x32_bf16 v[96:99], v[172:175], v[188:191], v[96:99]
	v_mfma_f32_16x16x32_bf16 v[84:87], v[164:167], v[198:201], v[84:87]
	v_mfma_f32_16x16x32_bf16 v[80:83], v[172:175], v[198:201], v[80:83]
	v_mfma_f32_16x16x32_bf16 v[68:71], v[164:167], v[206:209], v[68:71]
	v_mfma_f32_16x16x32_bf16 v[64:67], v[172:175], v[206:209], v[64:67]
	v_mfma_f32_16x16x32_bf16 v[116:119], v[168:171], v[184:187], v[116:119]
	v_mfma_f32_16x16x32_bf16 v[112:115], v[176:179], v[184:187], v[112:115]
	v_mfma_f32_16x16x32_bf16 v[100:103], v[168:171], v[194:197], v[100:103]
	v_mfma_f32_16x16x32_bf16 v[96:99], v[176:179], v[194:197], v[96:99]
	v_mfma_f32_16x16x32_bf16 v[84:87], v[168:171], v[202:205], v[84:87]
	v_mfma_f32_16x16x32_bf16 v[80:83], v[176:179], v[202:205], v[80:83]
	v_mfma_f32_16x16x32_bf16 v[68:71], v[168:171], v[212:215], v[68:71]
	v_mfma_f32_16x16x32_bf16 v[64:67], v[176:179], v[212:215], v[64:67]
	s_setprio 0
	s_barrier
; #define STAGE_A(bufoff, gbase) STAGEX(bufoff, gbase, voffA)
; #define STAGE_B(bufoff, gbase) STAGEX(bufoff, gbase, voffB)
; #define LDA(dst, b, h) do { _Pragma("unroll") for (int m = 0; m < 4; ++m) _Pragma("unroll") for (int k = 0; k < 2; ++k) dst[m][k] = *(const __attribute__((address_space(3))) bf16x8*)(lds + SA(b, h) + aoff + m * 2048 + k * 1024); } while (0)
; #define LDB(dst, b, h) do { _Pragma("unroll") for (int n = 0; n < 2; ++n) _Pragma("unroll") for (int k = 0; k < 2; ++k) dst[n][k] = *(const __attribute__((address_space(3))) bf16x8*)(lds + SB_(b, h) + boff + n * 2048 + k * 1024); } while (0)
; #define MMA(ai, bj, At, Bt_) do { __builtin_amdgcn_s_setprio(1); _Pragma("unroll") for (int m = 0; m < 4; ++m) _Pragma("unroll") for (int n = 0; n < 2; ++n) _Pragma("unroll") for (int k = 0; k < 2; ++k) \
;       acc[ai][bj][m][n] = __builtin_amdgcn_mfma_f32_16x16x32_bf16(Bt_[n][k], At[m][k], acc[ai][bj][m][n], 0, 0, 0); \
;     __builtin_amdgcn_s_setprio(0); } while (0)
; #define WAIT_V(n) asm volatile("s_waitcnt vmcnt(" #n ")" ::: "memory")
; #define WAIT_L(n) asm volatile("s_waitcnt lgkmcnt(" #n ")" ::: "memory")
; #define BAR __builtin_amdgcn_s_barrier()
; #define SCHED __builtin_amdgcn_sched_barrier(0)
; template <int MODE>
; DEV void gemm_phase(const bf16_t* __restrict__ A, const bf16_t* __restrict__ Bt, int M, int N, int K, bf16_t* __restrict__ Out, int ldo,
;                     const float* __restrict__ rstd, const float* __restrict__ rope) {
;     ...
;       LDA(At, 0, 1); STAGE_B(SB_(0, 0), b2); STAGE_B(SB_(0, 1), b2 + hstep); STAGE_A(SA(0, 0), a2);
;       WAIT_V(8); WAIT_L(0); BAR; MMA(1, 0, At, B0); MMA(1, 1, At, B1); BAR; SCHED;
;       LDB(B0, 1, 0); LDB(B1, 1, 1); SCHED; LDA(At, 1, 0); STAGE_A(SA(0, 1), a2 + hstep);
;       WAIT_V(8); WAIT_L(0); BAR; MMA(0, 0, At, B0); MMA(0, 1, At, B1); BAR; SCHED;
;       LDA(At, 1, 1); STAGE_B(SB_(1, 0), b3); STAGE_B(SB_(1, 1), b3 + hstep); STAGE_A(SA(1, 0), a3);
;       WAIT_V(8); WAIT_L(0); BAR; MMA(1, 0, At, B0); MMA(1, 1, At, B1); BAR; SCHED;
;     }
;     if (wr == 0) BAR;
	s_add_i32 s22, s43, s24
	v_lshl_add_u64 v[222:223], v[222:223], 0, s[46:47]
	s_mov_b32 m0, s22
	ds_read_b128 v[180:183], v146 offset:49152
	ds_read_b128 v[184:187], v146 offset:50176
	ds_read_b128 v[188:191], v146 offset:51200
	ds_read_b128 v[194:197], v146 offset:52224
	ds_read_b128 v[198:201], v146 offset:53248
	ds_read_b128 v[202:205], v146 offset:54272
	ds_read_b128 v[206:209], v146 offset:55296
	ds_read_b128 v[212:215], v146 offset:56320
	global_load_lds_dwordx4 v[222:223], off
	s_add_i32 m0, s22, 0x2000
	s_add_u32 s20, s20, 0x80080
	v_lshl_add_u64 v[222:223], v[224:225], 0, s[46:47]
	s_addc_u32 s21, s21, 0
	s_add_i32 s22, s44, s24
	global_load_lds_dwordx4 v[222:223], off
	v_lshl_add_u64 v[222:223], s[20:21], 0, v[192:193]
	s_mov_b32 m0, s22
	s_nop 0
	global_load_lds_dwordx4 v[222:223], off
	v_lshl_add_u64 v[222:223], s[20:21], 0, v[128:129]
	s_add_i32 m0, s22, 0x2000
	s_nop 0
	global_load_lds_dwordx4 v[222:223], off
	v_lshl_add_u64 v[222:223], v[226:227], 0, s[46:47]
	s_mov_b32 m0, s29
	s_nop 0
	global_load_lds_dwordx4 v[222:223], off
	v_lshl_add_u64 v[222:223], v[228:229], 0, s[46:47]
	s_mov_b32 m0, s30
	s_nop 0
	global_load_lds_dwordx4 v[222:223], off
	s_waitcnt vmcnt(8)
	s_waitcnt lgkmcnt(0)
	s_setprio 1
	s_barrier
	v_mfma_f32_16x16x32_bf16 v[60:63], v[148:151], v[180:183], v[60:63]
	v_mfma_f32_16x16x32_bf16 v[56:59], v[156:159], v[180:183], v[56:59]
	v_mfma_f32_16x16x32_bf16 v[44:47], v[148:151], v[188:191], v[44:47]
	v_mfma_f32_16x16x32_bf16 v[40:43], v[156:159], v[188:191], v[40:43]
	v_mfma_f32_16x16x32_bf16 v[28:31], v[148:151], v[198:201], v[28:31]
	v_mfma_f32_16x16x32_bf16 v[24:27], v[156:159], v[198:201], v[24:27]
	v_mfma_f32_16x16x32_bf16 v[12:15], v[148:151], v[206:209], v[12:15]
	v_mfma_f32_16x16x32_bf16 v[4:7], v[156:159], v[206:209], v[4:7]
	v_mfma_f32_16x16x32_bf16 v[60:63], v[152:155], v[184:187], v[60:63]
	v_mfma_f32_16x16x32_bf16 v[56:59], v[160:163], v[184:187], v[56:59]
	v_mfma_f32_16x16x32_bf16 v[44:47], v[152:155], v[194:197], v[44:47]
	v_mfma_f32_16x16x32_bf16 v[40:43], v[160:163], v[194:197], v[40:43]
	v_mfma_f32_16x16x32_bf16 v[28:31], v[152:155], v[202:205], v[28:31]
	v_mfma_f32_16x16x32_bf16 v[24:27], v[160:163], v[202:205], v[24:27]
	v_mfma_f32_16x16x32_bf16 v[12:15], v[152:155], v[212:215], v[12:15]
	v_mfma_f32_16x16x32_bf16 v[4:7], v[160:163], v[212:215], v[4:7]
	s_setprio 0
	s_setprio 1
	v_mfma_f32_16x16x32_bf16 v[52:55], v[164:167], v[180:183], v[52:55]
	v_mfma_f32_16x16x32_bf16 v[48:51], v[172:175], v[180:183], v[48:51]
	v_mfma_f32_16x16x32_bf16 v[36:39], v[164:167], v[188:191], v[36:39]
	v_mfma_f32_16x16x32_bf16 v[32:35], v[172:175], v[188:191], v[32:35]
	v_mfma_f32_16x16x32_bf16 v[20:23], v[164:167], v[198:201], v[20:23]
	v_mfma_f32_16x16x32_bf16 v[16:19], v[172:175], v[198:201], v[16:19]
	v_mfma_f32_16x16x32_bf16 v[8:11], v[164:167], v[206:209], v[8:11]
	v_mfma_f32_16x16x32_bf16 v[0:3], v[172:175], v[206:209], v[0:3]
	v_mfma_f32_16x16x32_bf16 v[52:55], v[168:171], v[184:187], v[52:55]
	v_mfma_f32_16x16x32_bf16 v[48:51], v[176:179], v[184:187], v[48:51]
	v_mfma_f32_16x16x32_bf16 v[36:39], v[168:171], v[194:197], v[36:39]
	v_mfma_f32_16x16x32_bf16 v[32:35], v[176:179], v[194:197], v[32:35]
	v_mfma_f32_16x16x32_bf16 v[20:23], v[168:171], v[202:205], v[20:23]
	v_mfma_f32_16x16x32_bf16 v[16:19], v[176:179], v[202:205], v[16:19]
	v_mfma_f32_16x16x32_bf16 v[8:11], v[168:171], v[212:215], v[8:11]
	v_mfma_f32_16x16x32_bf16 v[0:3], v[176:179], v[212:215], v[0:3]
	s_setprio 0
	s_barrier
	s_add_i32 s42, s42, 2
	s_add_u32 s18, s18, 0x100
	s_addc_u32 s19, s19, 0
	s_cmp_gt_u32 s42, 29
	s_cbranch_scc0 .LBB0_618
	s_and_b64 vcc, exec, s[6:7]
	s_cbranch_vccz .LBB0_621
	s_barrier

; #define STAGE_A(bufoff, gbase) STAGEX(bufoff, gbase, voffA)
; #define STAGE_B(bufoff, gbase) STAGEX(bufoff, gbase, voffB)
; #define LDA(dst, b, h) do { _Pragma("unroll") for (int m = 0; m < 4; ++m) _Pragma("unroll") for (int k = 0; k < 2; ++k) dst[m][k] = *(const __attribute__((address_space(3))) bf16x8*)(lds + SA(b, h) + aoff + m * 2048 + k * 1024); } while (0)
; #define LDB(dst, b, h) do { _Pragma("unroll") for (int n = 0; n < 2; ++n) _Pragma("unroll") for (int k = 0; k < 2; ++k) dst[n][k] = *(const __attribute__((address_space(3))) bf16x8*)(lds + SB_(b, h) + boff + n * 2048 + k * 1024); } while (0)
; #define MMA(ai, bj, At, Bt_) do { __builtin_amdgcn_s_setprio(1); _Pragma("unroll") for (int m = 0; m < 4; ++m) _Pragma("unroll") for (int n = 0; n < 2; ++n) _Pragma("unroll") for (int k = 0; k < 2; ++k) \
;       acc[ai][bj][m][n] = __builtin_amdgcn_mfma_f32_16x16x32_bf16(Bt_[n][k], At[m][k], acc[ai][bj][m][n], 0, 0, 0); \
;     __builtin_amdgcn_s_setprio(0); } while (0)
; #define WAIT_V(n) asm volatile("s_waitcnt vmcnt(" #n ")" ::: "memory")
; #define WAIT_L(n) asm volatile("s_waitcnt lgkmcnt(" #n ")" ::: "memory")
; #define BAR __builtin_amdgcn_s_barrier()
; #define SCHED __builtin_amdgcn_sched_barrier(0)
; template <int MODE>
; DEV void gemm_phase(const bf16_t* __restrict__ A, const bf16_t* __restrict__ Bt, int M, int N, int K, bf16_t* __restrict__ Out, int ldo,
;                     const float* __restrict__ rstd, const float* __restrict__ rope) {
;     ...
;     for (int t = 0; t < nt; t += 2) {
;       const bool last = (t == nt - 2);
;       const char* a1 = cA + (size_t)(t + 1) * 128;
;       const char* a2 = last ? nA : cA + (size_t)(t + 2) * 128; const char* b2 = last ? nB : cB + (size_t)(t + 2) * 128;
;       const char* a3 = a2 + 128; const char* b3 = b2 + 128;
;       LDB(B0, 0, 0); LDB(B1, 0, 1); SCHED; LDA(At, 0, 0); STAGE_A(SA(1, 1), a1 + hstep);
;       WAIT_V(8); WAIT_L(0); BAR; MMA(0, 0, At, B0); MMA(0, 1, At, B1); BAR; SCHED;
;       LDA(At, 0, 1); STAGE_B(SB_(0, 0), b2); STAGE_B(SB_(0, 1), b2 + hstep); STAGE_A(SA(0, 0), a2);
;       WAIT_V(8); WAIT_L(0); BAR; MMA(1, 0, At, B0); MMA(1, 1, At, B1); BAR; SCHED;
.LBB0_690:
	s_add_u32 s14, s12, 0x100
	s_addc_u32 s15, s13, 0
	s_add_i32 s39, 0, 0x10000
	s_cmpk_eq_i32 s38, 0x54
	s_cselect_b32 s19, s9, s15
	s_cselect_b32 s18, s8, s14
	v_add_u32_e32 v143, s39, v141
	s_cselect_b32 s17, s35, s37
	s_cselect_b32 s16, s34, s36
	s_add_i32 s40, 0, 0x14000
	ds_read_b128 v[144:147], v143
	ds_read_b128 v[148:151], v143 offset:1024
	ds_read_b128 v[152:155], v143 offset:2048
	ds_read_b128 v[156:159], v143 offset:3072
	v_add_u32_e32 v143, s40, v141
	ds_read_b128 v[160:163], v143
	ds_read_b128 v[164:167], v143 offset:1024
	ds_read_b128 v[168:171], v143 offset:2048
	ds_read_b128 v[172:175], v143 offset:3072
	v_lshl_add_u64 v[212:213], s[12:13], 0, v[136:137]
	s_add_i32 m0, s21, 0xc000
	ds_read_b128 v[176:179], v142
	ds_read_b128 v[180:183], v142 offset:1024
	ds_read_b128 v[184:187], v142 offset:2048
	ds_read_b128 v[188:191], v142 offset:3072
	ds_read_b128 v[194:197], v142 offset:4096
	ds_read_b128 v[198:201], v142 offset:5120
	ds_read_b128 v[202:205], v142 offset:6144
	ds_read_b128 v[206:209], v142 offset:7168
	global_load_lds_dwordx4 v[212:213], off
	v_lshl_add_u64 v[212:213], s[12:13], 0, v[138:139]
	s_add_i32 m0, s21, 0xe000
	s_nop 0
	global_load_lds_dwordx4 v[212:213], off
	s_waitcnt vmcnt(8)
	s_waitcnt lgkmcnt(0)
	s_setprio 1
	s_barrier
	v_mfma_f32_16x16x32_bf16 v[124:127], v[144:147], v[176:179], v[124:127]
	v_mfma_f32_16x16x32_bf16 v[120:123], v[152:155], v[176:179], v[120:123]
	v_mfma_f32_16x16x32_bf16 v[116:119], v[144:147], v[184:187], v[116:119]
	v_mfma_f32_16x16x32_bf16 v[112:115], v[152:155], v[184:187], v[112:115]
	v_mfma_f32_16x16x32_bf16 v[100:103], v[144:147], v[194:197], v[100:103]
	v_mfma_f32_16x16x32_bf16 v[96:99], v[152:155], v[194:197], v[96:99]
	v_mfma_f32_16x16x32_bf16 v[84:87], v[144:147], v[202:205], v[84:87]
	v_mfma_f32_16x16x32_bf16 v[80:83], v[152:155], v[202:205], v[80:83]
	v_mfma_f32_16x16x32_bf16 v[124:127], v[148:151], v[180:183], v[124:127]
	v_mfma_f32_16x16x32_bf16 v[120:123], v[156:159], v[180:183], v[120:123]
	v_mfma_f32_16x16x32_bf16 v[116:119], v[148:151], v[188:191], v[116:119]
	v_mfma_f32_16x16x32_bf16 v[112:115], v[156:159], v[188:191], v[112:115]
	v_mfma_f32_16x16x32_bf16 v[100:103], v[148:151], v[198:201], v[100:103]
	v_mfma_f32_16x16x32_bf16 v[96:99], v[156:159], v[198:201], v[96:99]
	v_mfma_f32_16x16x32_bf16 v[84:87], v[148:151], v[206:209], v[84:87]
	v_mfma_f32_16x16x32_bf16 v[80:83], v[156:159], v[206:209], v[80:83]
	s_setprio 0
	s_setprio 1
	v_mfma_f32_16x16x32_bf16 v[108:111], v[160:163], v[176:179], v[108:111]
	v_mfma_f32_16x16x32_bf16 v[104:107], v[168:171], v[176:179], v[104:107]
	v_mfma_f32_16x16x32_bf16 v[92:95], v[160:163], v[184:187], v[92:95]
	v_mfma_f32_16x16x32_bf16 v[88:91], v[168:171], v[184:187], v[88:91]
	v_mfma_f32_16x16x32_bf16 v[76:79], v[160:163], v[194:197], v[76:79]
	v_mfma_f32_16x16x32_bf16 v[72:75], v[168:171], v[194:197], v[72:75]
	v_mfma_f32_16x16x32_bf16 v[68:71], v[160:163], v[202:205], v[68:71]
	v_mfma_f32_16x16x32_bf16 v[64:67], v[168:171], v[202:205], v[64:67]
	v_mfma_f32_16x16x32_bf16 v[108:111], v[164:167], v[180:183], v[108:111]
	v_mfma_f32_16x16x32_bf16 v[104:107], v[172:175], v[180:183], v[104:107]
	v_mfma_f32_16x16x32_bf16 v[92:95], v[164:167], v[188:191], v[92:95]
	v_mfma_f32_16x16x32_bf16 v[88:91], v[172:175], v[188:191], v[88:91]
	v_mfma_f32_16x16x32_bf16 v[76:79], v[164:167], v[198:201], v[76:79]
	v_mfma_f32_16x16x32_bf16 v[72:75], v[172:175], v[198:201], v[72:75]
	v_mfma_f32_16x16x32_bf16 v[68:71], v[164:167], v[206:209], v[68:71]
	v_mfma_f32_16x16x32_bf16 v[64:67], v[172:175], v[206:209], v[64:67]
	s_setprio 0
	s_barrier
	s_add_i32 s12, s39, s20
	v_lshl_add_u64 v[212:213], s[16:17], 0, v[192:193]
	s_mov_b32 m0, s12
	ds_read_b128 v[176:179], v142 offset:16384
	ds_read_b128 v[180:183], v142 offset:17408
	ds_read_b128 v[184:187], v142 offset:18432
	ds_read_b128 v[188:191], v142 offset:19456
	ds_read_b128 v[194:197], v142 offset:20480
	ds_read_b128 v[198:201], v142 offset:21504
	ds_read_b128 v[202:205], v142 offset:22528
	ds_read_b128 v[206:209], v142 offset:23552
	global_load_lds_dwordx4 v[212:213], off
	s_add_i32 m0, s12, 0x2000
	s_add_u32 s12, s16, 0x160000
	v_lshl_add_u64 v[214:215], s[16:17], 0, v[128:129]
	s_addc_u32 s13, s17, 0
	s_add_i32 s39, s40, s20
	global_load_lds_dwordx4 v[214:215], off
	v_lshl_add_u64 v[222:223], s[12:13], 0, v[192:193]
	s_mov_b32 m0, s39
	v_lshl_add_u64 v[224:225], s[18:19], 0, v[130:131]
	global_load_lds_dwordx4 v[222:223], off
	v_lshl_add_u64 v[222:223], s[12:13], 0, v[128:129]
	s_add_i32 m0, s39, 0x2000
	s_nop 0
	global_load_lds_dwordx4 v[222:223], off
	v_lshl_add_u64 v[222:223], s[18:19], 0, v[132:133]
	s_mov_b32 m0, s21
	s_nop 0
	global_load_lds_dwordx4 v[222:223], off
	s_mov_b32 m0, s22
	s_nop 0
	global_load_lds_dwordx4 v[224:225], off
	s_waitcnt vmcnt(8)
	s_waitcnt lgkmcnt(0)
	s_setprio 1
	s_barrier
; #define STAGE_A(bufoff, gbase) STAGEX(bufoff, gbase, voffA)
; #define STAGE_B(bufoff, gbase) STAGEX(bufoff, gbase, voffB)
; #define LDA(dst, b, h) do { _Pragma("unroll") for (int m = 0; m < 4; ++m) _Pragma("unroll") for (int k = 0; k < 2; ++k) dst[m][k] = *(const __attribute__((address_space(3))) bf16x8*)(lds + SA(b, h) + aoff + m * 2048 + k * 1024); } while (0)
; #define LDB(dst, b, h) do { _Pragma("unroll") for (int n = 0; n < 2; ++n) _Pragma("unroll") for (int k = 0; k < 2; ++k) dst[n][k] = *(const __attribute__((address_space(3))) bf16x8*)(lds + SB_(b, h) + boff + n * 2048 + k * 1024); } while (0)
; #define MMA(ai, bj, At, Bt_) do { __builtin_amdgcn_s_setprio(1); _Pragma("unroll") for (int m = 0; m < 4; ++m) _Pragma("unroll") for (int n = 0; n < 2; ++n) _Pragma("unroll") for (int k = 0; k < 2; ++k) \
;       acc[ai][bj][m][n] = __builtin_amdgcn_mfma_f32_16x16x32_bf16(Bt_[n][k], At[m][k], acc[ai][bj][m][n], 0, 0, 0); \
;     __builtin_amdgcn_s_setprio(0); } while (0)
; #define WAIT_V(n) asm volatile("s_waitcnt vmcnt(" #n ")" ::: "memory")
; #define WAIT_L(n) asm volatile("s_waitcnt lgkmcnt(" #n ")" ::: "memory")
; #define BAR __builtin_amdgcn_s_barrier()
; #define SCHED __builtin_amdgcn_sched_barrier(0)
; template <int MODE>
; DEV void gemm_phase(const bf16_t* __restrict__ A, const bf16_t* __restrict__ Bt, int M, int N, int K, bf16_t* __restrict__ Out, int ldo,
;                     const float* __restrict__ rstd, const float* __restrict__ rope) {
;     ...
;       LDB(B0, 0, 0); LDB(B1, 0, 1); SCHED; LDA(At, 0, 0); STAGE_A(SA(1, 1), a1 + hstep);
;       WAIT_V(8); WAIT_L(0); BAR; MMA(0, 0, At, B0); MMA(0, 1, At, B1); BAR; SCHED;
;       LDA(At, 0, 1); STAGE_B(SB_(0, 0), b2); STAGE_B(SB_(0, 1), b2 + hstep); STAGE_A(SA(0, 0), a2);
;       WAIT_V(8); WAIT_L(0); BAR; MMA(1, 0, At, B0); MMA(1, 1, At, B1); BAR; SCHED;
;       LDB(B0, 1, 0); LDB(B1, 1, 1); SCHED; LDA(At, 1, 0); STAGE_A(SA(0, 1), a2 + hstep);
;       WAIT_V(8); WAIT_L(0); BAR; MMA(0, 0, At, B0); MMA(0, 1, At, B1); BAR; SCHED;
;       LDA(At, 1, 1); STAGE_B(SB_(1, 0), b3); STAGE_B(SB_(1, 1), b3 + hstep); STAGE_A(SA(1, 0), a3);
;       WAIT_V(8); WAIT_L(0); BAR; MMA(1, 0, At, B0); MMA(1, 1, At, B1); BAR; SCHED;
	v_mfma_f32_16x16x32_bf16 v[60:63], v[144:147], v[176:179], v[60:63]
	v_mfma_f32_16x16x32_bf16 v[56:59], v[152:155], v[176:179], v[56:59]
	v_mfma_f32_16x16x32_bf16 v[52:55], v[144:147], v[184:187], v[52:55]
	v_mfma_f32_16x16x32_bf16 v[48:51], v[152:155], v[184:187], v[48:51]
	v_mfma_f32_16x16x32_bf16 v[36:39], v[144:147], v[194:197], v[36:39]
	v_mfma_f32_16x16x32_bf16 v[32:35], v[152:155], v[194:197], v[32:35]
	v_mfma_f32_16x16x32_bf16 v[20:23], v[144:147], v[202:205], v[20:23]
	v_mfma_f32_16x16x32_bf16 v[16:19], v[152:155], v[202:205], v[16:19]
	v_mfma_f32_16x16x32_bf16 v[60:63], v[148:151], v[180:183], v[60:63]
	v_mfma_f32_16x16x32_bf16 v[56:59], v[156:159], v[180:183], v[56:59]
	v_mfma_f32_16x16x32_bf16 v[52:55], v[148:151], v[188:191], v[52:55]
	v_mfma_f32_16x16x32_bf16 v[48:51], v[156:159], v[188:191], v[48:51]
	v_mfma_f32_16x16x32_bf16 v[36:39], v[148:151], v[198:201], v[36:39]
	v_mfma_f32_16x16x32_bf16 v[32:35], v[156:159], v[198:201], v[32:35]
	v_mfma_f32_16x16x32_bf16 v[20:23], v[148:151], v[206:209], v[20:23]
	v_mfma_f32_16x16x32_bf16 v[16:19], v[156:159], v[206:209], v[16:19]
	s_setprio 0
	s_setprio 1
	v_mfma_f32_16x16x32_bf16 v[44:47], v[160:163], v[176:179], v[44:47]
	v_mfma_f32_16x16x32_bf16 v[40:43], v[168:171], v[176:179], v[40:43]
	v_mfma_f32_16x16x32_bf16 v[28:31], v[160:163], v[184:187], v[28:31]
	v_mfma_f32_16x16x32_bf16 v[24:27], v[168:171], v[184:187], v[24:27]
	v_mfma_f32_16x16x32_bf16 v[12:15], v[160:163], v[194:197], v[12:15]
	v_mfma_f32_16x16x32_bf16 v[8:11], v[168:171], v[194:197], v[8:11]
	v_mfma_f32_16x16x32_bf16 v[4:7], v[160:163], v[202:205], v[4:7]
	v_mfma_f32_16x16x32_bf16 v[0:3], v[168:171], v[202:205], v[0:3]
	v_mfma_f32_16x16x32_bf16 v[44:47], v[164:167], v[180:183], v[44:47]
	v_mfma_f32_16x16x32_bf16 v[40:43], v[172:175], v[180:183], v[40:43]
	v_mfma_f32_16x16x32_bf16 v[28:31], v[164:167], v[188:191], v[28:31]
	v_mfma_f32_16x16x32_bf16 v[24:27], v[172:175], v[188:191], v[24:27]
	v_mfma_f32_16x16x32_bf16 v[12:15], v[164:167], v[198:201], v[12:15]
	v_mfma_f32_16x16x32_bf16 v[8:11], v[172:175], v[198:201], v[8:11]
	v_mfma_f32_16x16x32_bf16 v[4:7], v[164:167], v[206:209], v[4:7]
	v_mfma_f32_16x16x32_bf16 v[0:3], v[172:175], v[206:209], v[0:3]
	s_setprio 0
	s_barrier
	s_add_i32 s39, 0, 0x18000
	v_add_u32_e32 v143, s39, v141
	s_add_i32 s40, 0, 0x1c000
	ds_read_b128 v[144:147], v143
	ds_read_b128 v[148:151], v143 offset:1024
	ds_read_b128 v[152:155], v143 offset:2048
	ds_read_b128 v[156:159], v143 offset:3072
	v_add_u32_e32 v143, s40, v141
	ds_read_b128 v[160:163], v143
	ds_read_b128 v[164:167], v143 offset:1024
	ds_read_b128 v[168:171], v143 offset:2048
	ds_read_b128 v[172:175], v143 offset:3072
	s_add_u32 s12, s18, 0x160000
	s_addc_u32 s13, s19, 0
	s_mov_b32 m0, s23
	v_lshl_add_u64 v[226:227], s[12:13], 0, v[132:133]
	ds_read_b128 v[176:179], v142 offset:32768
	ds_read_b128 v[180:183], v142 offset:33792
	ds_read_b128 v[184:187], v142 offset:34816
	ds_read_b128 v[188:191], v142 offset:35840
	ds_read_b128 v[194:197], v142 offset:36864
	ds_read_b128 v[198:201], v142 offset:37888
	ds_read_b128 v[202:205], v142 offset:38912
	ds_read_b128 v[206:209], v142 offset:39936
	global_load_lds_dwordx4 v[226:227], off
	v_lshl_add_u64 v[226:227], s[12:13], 0, v[130:131]
	s_mov_b32 m0, s24
	s_nop 0
	global_load_lds_dwordx4 v[226:227], off
	s_waitcnt vmcnt(8)
	s_waitcnt lgkmcnt(0)
	s_setprio 1
	s_barrier
	v_mfma_f32_16x16x32_bf16 v[124:127], v[144:147], v[176:179], v[124:127]
	v_mfma_f32_16x16x32_bf16 v[120:123], v[152:155], v[176:179], v[120:123]
	v_mfma_f32_16x16x32_bf16 v[116:119], v[144:147], v[184:187], v[116:119]
	v_mfma_f32_16x16x32_bf16 v[112:115], v[152:155], v[184:187], v[112:115]
	v_mfma_f32_16x16x32_bf16 v[100:103], v[144:147], v[194:197], v[100:103]
	v_mfma_f32_16x16x32_bf16 v[96:99], v[152:155], v[194:197], v[96:99]
	v_mfma_f32_16x16x32_bf16 v[84:87], v[144:147], v[202:205], v[84:87]
	v_mfma_f32_16x16x32_bf16 v[80:83], v[152:155], v[202:205], v[80:83]
	v_mfma_f32_16x16x32_bf16 v[124:127], v[148:151], v[180:183], v[124:127]
	v_mfma_f32_16x16x32_bf16 v[120:123], v[156:159], v[180:183], v[120:123]
	v_mfma_f32_16x16x32_bf16 v[116:119], v[148:151], v[188:191], v[116:119]
	v_mfma_f32_16x16x32_bf16 v[112:115], v[156:159], v[188:191], v[112:115]
	v_mfma_f32_16x16x32_bf16 v[100:103], v[148:151], v[198:201], v[100:103]
	v_mfma_f32_16x16x32_bf16 v[96:99], v[156:159], v[198:201], v[96:99]
	v_mfma_f32_16x16x32_bf16 v[84:87], v[148:151], v[206:209], v[84:87]
	v_mfma_f32_16x16x32_bf16 v[80:83], v[156:159], v[206:209], v[80:83]
	s_setprio 0
	s_setprio 1
	v_mfma_f32_16x16x32_bf16 v[108:111], v[160:163], v[176:179], v[108:111]
	v_mfma_f32_16x16x32_bf16 v[104:107], v[168:171], v[176:179], v[104:107]
	v_mfma_f32_16x16x32_bf16 v[92:95], v[160:163], v[184:187], v[92:95]
	v_mfma_f32_16x16x32_bf16 v[88:91], v[168:171], v[184:187], v[88:91]
	v_mfma_f32_16x16x32_bf16 v[76:79], v[160:163], v[194:197], v[76:79]
	v_mfma_f32_16x16x32_bf16 v[72:75], v[168:171], v[194:197], v[72:75]
	v_mfma_f32_16x16x32_bf16 v[68:71], v[160:163], v[202:205], v[68:71]
	v_mfma_f32_16x16x32_bf16 v[64:67], v[168:171], v[202:205], v[64:67]
	v_mfma_f32_16x16x32_bf16 v[108:111], v[164:167], v[180:183], v[108:111]
	v_mfma_f32_16x16x32_bf16 v[104:107], v[172:175], v[180:183], v[104:107]
	v_mfma_f32_16x16x32_bf16 v[92:95], v[164:167], v[188:191], v[92:95]
	v_mfma_f32_16x16x32_bf16 v[88:91], v[172:175], v[188:191], v[88:91]
	v_mfma_f32_16x16x32_bf16 v[76:79], v[164:167], v[198:201], v[76:79]
	v_mfma_f32_16x16x32_bf16 v[72:75], v[172:175], v[198:201], v[72:75]
	v_mfma_f32_16x16x32_bf16 v[68:71], v[164:167], v[206:209], v[68:71]
	v_mfma_f32_16x16x32_bf16 v[64:67], v[172:175], v[206:209], v[64:67]
	s_setprio 0
	s_barrier
; #define STAGE_A(bufoff, gbase) STAGEX(bufoff, gbase, voffA)
; #define STAGE_B(bufoff, gbase) STAGEX(bufoff, gbase, voffB)
; #define LDA(dst, b, h) do { _Pragma("unroll") for (int m = 0; m < 4; ++m) _Pragma("unroll") for (int k = 0; k < 2; ++k) dst[m][k] = *(const __attribute__((address_space(3))) bf16x8*)(lds + SA(b, h) + aoff + m * 2048 + k * 1024); } while (0)
; #define LDB(dst, b, h) do { _Pragma("unroll") for (int n = 0; n < 2; ++n) _Pragma("unroll") for (int k = 0; k < 2; ++k) dst[n][k] = *(const __attribute__((address_space(3))) bf16x8*)(lds + SB_(b, h) + boff + n * 2048 + k * 1024); } while (0)
; #define MMA(ai, bj, At, Bt_) do { __builtin_amdgcn_s_setprio(1); _Pragma("unroll") for (int m = 0; m < 4; ++m) _Pragma("unroll") for (int n = 0; n < 2; ++n) _Pragma("unroll") for (int k = 0; k < 2; ++k) \
;       acc[ai][bj][m][n] = __builtin_amdgcn_mfma_f32_16x16x32_bf16(Bt_[n][k], At[m][k], acc[ai][bj][m][n], 0, 0, 0); \
;     __builtin_amdgcn_s_setprio(0); } while (0)
; #define WAIT_V(n) asm volatile("s_waitcnt vmcnt(" #n ")" ::: "memory")
; #define WAIT_L(n) asm volatile("s_waitcnt lgkmcnt(" #n ")" ::: "memory")
; #define BAR __builtin_amdgcn_s_barrier()
; #define SCHED __builtin_amdgcn_sched_barrier(0)
; template <int MODE>
; DEV void gemm_phase(const bf16_t* __restrict__ A, const bf16_t* __restrict__ Bt, int M, int N, int K, bf16_t* __restrict__ Out, int ldo,
;                     const float* __restrict__ rstd, const float* __restrict__ rope) {
;     ...
;       LDA(At, 0, 1); STAGE_B(SB_(0, 0), b2); STAGE_B(SB_(0, 1), b2 + hstep); STAGE_A(SA(0, 0), a2);
;       WAIT_V(8); WAIT_L(0); BAR; MMA(1, 0, At, B0); MMA(1, 1, At, B1); BAR; SCHED;
;       LDB(B0, 1, 0); LDB(B1, 1, 1); SCHED; LDA(At, 1, 0); STAGE_A(SA(0, 1), a2 + hstep);
;       WAIT_V(8); WAIT_L(0); BAR; MMA(0, 0, At, B0); MMA(0, 1, At, B1); BAR; SCHED;
;       LDA(At, 1, 1); STAGE_B(SB_(1, 0), b3); STAGE_B(SB_(1, 1), b3 + hstep); STAGE_A(SA(1, 0), a3);
;       WAIT_V(8); WAIT_L(0); BAR; MMA(1, 0, At, B0); MMA(1, 1, At, B1); BAR; SCHED;
;     }
;     if (wr == 0) BAR;
	s_add_i32 s12, s39, s20
	v_lshl_add_u64 v[212:213], v[212:213], 0, s[42:43]
	s_mov_b32 m0, s12
	ds_read_b128 v[176:179], v142 offset:49152
	ds_read_b128 v[180:183], v142 offset:50176
	ds_read_b128 v[184:187], v142 offset:51200
	ds_read_b128 v[188:191], v142 offset:52224
	ds_read_b128 v[194:197], v142 offset:53248
	ds_read_b128 v[198:201], v142 offset:54272
	ds_read_b128 v[202:205], v142 offset:55296
	ds_read_b128 v[206:209], v142 offset:56320
	global_load_lds_dwordx4 v[212:213], off
	s_add_i32 m0, s12, 0x2000
	s_add_u32 s12, s16, 0x160080
	v_lshl_add_u64 v[212:213], v[214:215], 0, s[42:43]
	s_addc_u32 s13, s17, 0
	s_add_i32 s16, s40, s20
	global_load_lds_dwordx4 v[212:213], off
	v_lshl_add_u64 v[212:213], s[12:13], 0, v[192:193]
	s_mov_b32 m0, s16
	s_nop 0
	global_load_lds_dwordx4 v[212:213], off
	v_lshl_add_u64 v[212:213], s[12:13], 0, v[128:129]
	s_add_i32 m0, s16, 0x2000
	s_nop 0
	global_load_lds_dwordx4 v[212:213], off
	v_lshl_add_u64 v[212:213], v[222:223], 0, s[42:43]
	s_mov_b32 m0, s25
	s_nop 0
	global_load_lds_dwordx4 v[212:213], off
	v_lshl_add_u64 v[212:213], v[224:225], 0, s[42:43]
	s_mov_b32 m0, s26
	s_nop 0
	global_load_lds_dwordx4 v[212:213], off
	s_waitcnt vmcnt(8)
	s_waitcnt lgkmcnt(0)
	s_setprio 1
	s_barrier
	v_mfma_f32_16x16x32_bf16 v[60:63], v[144:147], v[176:179], v[60:63]
	v_mfma_f32_16x16x32_bf16 v[56:59], v[152:155], v[176:179], v[56:59]
	v_mfma_f32_16x16x32_bf16 v[52:55], v[144:147], v[184:187], v[52:55]
	v_mfma_f32_16x16x32_bf16 v[48:51], v[152:155], v[184:187], v[48:51]
	v_mfma_f32_16x16x32_bf16 v[36:39], v[144:147], v[194:197], v[36:39]
	v_mfma_f32_16x16x32_bf16 v[32:35], v[152:155], v[194:197], v[32:35]
	v_mfma_f32_16x16x32_bf16 v[20:23], v[144:147], v[202:205], v[20:23]
	v_mfma_f32_16x16x32_bf16 v[16:19], v[152:155], v[202:205], v[16:19]
	v_mfma_f32_16x16x32_bf16 v[60:63], v[148:151], v[180:183], v[60:63]
	v_mfma_f32_16x16x32_bf16 v[56:59], v[156:159], v[180:183], v[56:59]
	v_mfma_f32_16x16x32_bf16 v[52:55], v[148:151], v[188:191], v[52:55]
	v_mfma_f32_16x16x32_bf16 v[48:51], v[156:159], v[188:191], v[48:51]
	v_mfma_f32_16x16x32_bf16 v[36:39], v[148:151], v[198:201], v[36:39]
	v_mfma_f32_16x16x32_bf16 v[32:35], v[156:159], v[198:201], v[32:35]
	v_mfma_f32_16x16x32_bf16 v[20:23], v[148:151], v[206:209], v[20:23]
	v_mfma_f32_16x16x32_bf16 v[16:19], v[156:159], v[206:209], v[16:19]
	s_setprio 0
	s_setprio 1
	v_mfma_f32_16x16x32_bf16 v[44:47], v[160:163], v[176:179], v[44:47]
	v_mfma_f32_16x16x32_bf16 v[40:43], v[168:171], v[176:179], v[40:43]
	v_mfma_f32_16x16x32_bf16 v[28:31], v[160:163], v[184:187], v[28:31]
	v_mfma_f32_16x16x32_bf16 v[24:27], v[168:171], v[184:187], v[24:27]
	v_mfma_f32_16x16x32_bf16 v[12:15], v[160:163], v[194:197], v[12:15]
	v_mfma_f32_16x16x32_bf16 v[8:11], v[168:171], v[194:197], v[8:11]
	v_mfma_f32_16x16x32_bf16 v[4:7], v[160:163], v[202:205], v[4:7]
	v_mfma_f32_16x16x32_bf16 v[0:3], v[168:171], v[202:205], v[0:3]
	v_mfma_f32_16x16x32_bf16 v[44:47], v[164:167], v[180:183], v[44:47]
	v_mfma_f32_16x16x32_bf16 v[40:43], v[172:175], v[180:183], v[40:43]
	v_mfma_f32_16x16x32_bf16 v[28:31], v[164:167], v[188:191], v[28:31]
	v_mfma_f32_16x16x32_bf16 v[24:27], v[172:175], v[188:191], v[24:27]
	v_mfma_f32_16x16x32_bf16 v[12:15], v[164:167], v[198:201], v[12:15]
	v_mfma_f32_16x16x32_bf16 v[8:11], v[172:175], v[198:201], v[8:11]
	v_mfma_f32_16x16x32_bf16 v[4:7], v[164:167], v[206:209], v[4:7]
	v_mfma_f32_16x16x32_bf16 v[0:3], v[172:175], v[206:209], v[0:3]
	s_setprio 0
	s_barrier
	s_add_i32 s38, s38, 2
	s_add_u32 s36, s36, 0x100
	s_addc_u32 s37, s37, 0
	s_cmpk_gt_u32 s38, 0x55
	s_mov_b64 s[12:13], s[14:15]
	s_cbranch_scc0 .LBB0_690
	s_and_b64 vcc, exec, s[4:5]
	s_cbranch_vccz .LBB0_693
	s_barrier
